# K-loop schedule: B-fragment reads issued one phase earlier (balanced 8/4/8/4 LDS reads per phase), rolling vmcnt(10) every phase; in-proj unit order swap pn5/pn7
# speedup vs baseline: 1.0204x; 1.0043x over previous
.LBB0_69:
	s_add_i32 m0, s3, 0x18000
	v_lshl_add_u64 v[0:1], v[0:1], 0, s[66:67]
	s_waitcnt vmcnt(4)
	s_barrier
	global_load_lds_dwordx4 v[0:1], off
	v_lshl_add_u64 v[0:1], v[2:3], 0, s[66:67]
	s_add_i32 m0, s3, 0x1a000
	s_add_i32 s30, s3, 0x8000
	global_load_lds_dwordx4 v[0:1], off
	v_lshl_add_u64 v[0:1], v[4:5], 0, s[66:67]
	s_mov_b32 m0, s30
	s_add_i32 s31, s3, 0xa000
	global_load_lds_dwordx4 v[0:1], off
	v_lshl_add_u64 v[0:1], v[6:7], 0, s[66:67]
	s_mov_b32 m0, s31
	v_and_b32_e32 v19, 15, v15
	global_load_lds_dwordx4 v[0:1], off
	s_add_i32 m0, s3, 0x1c000
	v_lshl_add_u64 v[0:1], v[8:9], 0, s[66:67]
	global_load_lds_dwordx4 v[0:1], off
	v_lshl_add_u64 v[0:1], v[10:11], 0, s[66:67]
	s_add_i32 m0, s3, 0x1e000
	v_and_b32_e32 v20, 48, v15
	global_load_lds_dwordx4 v[0:1], off
	v_lshlrev_b32_e32 v19, 6, v19
	v_lshlrev_b32_e32 v15, 2, v15
	s_lshr_b32 s29, s19, 6
	v_or_b32_e32 v21, v19, v20
	s_lshl_b32 s19, s23, 13
	v_and_b32_e32 v15, 32, v15
	v_bitop3_b32 v19, v19, v15, v20 bitop3:0x36
	v_bitop3_b32 v15, v21, s19, v15 bitop3:0xde
	s_lshl_b32 s19, s22, 12
	s_and_b32 s19, s19, 0x3000
	s_add_i32 s34, s29, -2
	s_add_u32 s16, s18, s16
	s_addc_u32 s17, 0, s17
	s_add_u32 s12, s16, s12
	s_addc_u32 s13, s17, s13
	s_add_u32 s12, s12, s25
	s_addc_u32 s13, s13, 0
	s_add_u32 s12, s80, s12
	s_addc_u32 s13, s81, s13
	v_add_u32_e32 v0, v16, v17
	s_add_u32 s12, s12, 0x80
	v_add_lshl_u32 v0, v0, v18, 1
	v_mov_b32_e32 v1, v133
	s_addc_u32 s13, s13, 0
	v_lshl_add_u64 v[130:131], s[12:13], 0, v[0:1]
	v_add_u32_e32 v0, v12, v13
	s_waitcnt vmcnt(6)
	v_add_lshl_u32 v0, v0, v14, 1
	v_lshl_add_u64 v[150:151], s[12:13], 0, v[0:1]
	v_mov_b32_e32 v0, 0
	v_or_b32_e32 v152, s19, v19
	s_mov_b32 s18, 0
	s_mov_b64 s[12:13], 0
	v_add_u32_e32 v153, 0, v15
	v_mov_b32_e32 v1, v0
	v_mov_b64_e32 v[2:3], 0
	v_mov_b64_e32 v[4:5], 0
	v_mov_b64_e32 v[6:7], 0
	v_mov_b64_e32 v[8:9], 0
	v_mov_b64_e32 v[10:11], 0
	v_mov_b64_e32 v[12:13], 0
	v_mov_b64_e32 v[14:15], 0
	v_mov_b64_e32 v[16:17], 0
	v_mov_b64_e32 v[18:19], 0
	v_mov_b64_e32 v[20:21], 0
	v_mov_b64_e32 v[22:23], 0
	v_mov_b64_e32 v[24:25], 0
	v_mov_b64_e32 v[26:27], 0
	v_mov_b64_e32 v[28:29], 0
	v_mov_b64_e32 v[30:31], 0
	v_mov_b64_e32 v[32:33], 0
	v_mov_b64_e32 v[34:35], 0
	v_mov_b64_e32 v[36:37], 0
	v_mov_b64_e32 v[38:39], 0
	v_mov_b64_e32 v[40:41], 0
	v_mov_b64_e32 v[42:43], 0
	v_mov_b64_e32 v[44:45], 0
	v_mov_b64_e32 v[46:47], 0
	v_mov_b64_e32 v[48:49], 0
	v_mov_b64_e32 v[50:51], 0
	v_mov_b64_e32 v[52:53], 0
	v_mov_b64_e32 v[54:55], 0
	v_mov_b64_e32 v[56:57], 0
	v_mov_b64_e32 v[58:59], 0
	v_mov_b64_e32 v[60:61], 0
	v_mov_b64_e32 v[62:63], 0
	v_mov_b64_e32 v[64:65], 0
	v_mov_b64_e32 v[66:67], 0
	v_mov_b64_e32 v[68:69], 0
	v_mov_b64_e32 v[70:71], 0
	v_mov_b64_e32 v[72:73], 0
	v_mov_b64_e32 v[74:75], 0
	v_mov_b64_e32 v[76:77], 0
	v_mov_b64_e32 v[78:79], 0
	v_mov_b64_e32 v[80:81], 0
	v_mov_b64_e32 v[82:83], 0
	v_mov_b64_e32 v[84:85], 0
	v_mov_b64_e32 v[86:87], 0
	v_mov_b64_e32 v[88:89], 0
	v_mov_b64_e32 v[90:91], 0
	v_mov_b64_e32 v[92:93], 0
	v_mov_b64_e32 v[94:95], 0
	v_mov_b64_e32 v[96:97], 0
	v_mov_b64_e32 v[98:99], 0
	v_mov_b64_e32 v[100:101], 0
	v_mov_b64_e32 v[102:103], 0
	v_mov_b64_e32 v[104:105], 0
	v_mov_b64_e32 v[106:107], 0
	v_mov_b64_e32 v[108:109], 0
	v_mov_b64_e32 v[110:111], 0
	v_mov_b64_e32 v[112:113], 0
	v_mov_b64_e32 v[114:115], 0
	v_mov_b64_e32 v[116:117], 0
	v_mov_b64_e32 v[118:119], 0
	v_mov_b64_e32 v[120:121], 0
	v_mov_b64_e32 v[122:123], 0
	v_mov_b64_e32 v[124:125], 0
	v_mov_b64_e32 v[126:127], 0
	s_barrier
	v_add_u32_e32 v166, 0x10000, v152
	ds_read_b128 v[154:157], v166
	ds_read_b128 v[158:161], v166 offset:1024
	ds_read_b128 v[162:165], v166 offset:2048
	ds_read_b128 v[166:169], v166 offset:3072
.LBB0_70:
	s_add_i32 s35, s18, 2
	s_add_u32 s16, s12, 0x100
	s_addc_u32 s17, s13, 0
	s_cmp_lg_u32 s34, s18
	s_cselect_b32 s22, s16, 0
	s_cselect_b32 s23, s17, 0
	s_add_u32 s18, s10, s22
	s_addc_u32 s19, s11, s23
	s_add_i32 s36, 0, 0x10000
	s_add_u32 s22, s8, s22
	s_addc_u32 s23, s9, s23
	v_lshl_add_u64 v[190:191], v[130:131], 0, s[12:13]
	s_add_i32 m0, s3, 0xc000
	ds_read_b128 v[170:173], v153
	ds_read_b128 v[178:181], v153 offset:2048
	ds_read_b128 v[186:189], v153 offset:4096
	ds_read_b128 v[220:223], v153 offset:6144
	ds_read_b128 v[174:177], v153 offset:1024
	ds_read_b128 v[182:185], v153 offset:3072
	ds_read_b128 v[216:219], v153 offset:5120
	ds_read_b128 v[224:227], v153 offset:7168
	global_load_lds_dwordx4 v[190:191], off
	v_lshl_add_u64 v[190:191], v[150:151], 0, s[12:13]
	s_add_i32 m0, s3, 0xe000
	s_nop 0
	global_load_lds_dwordx4 v[190:191], off
	s_waitcnt lgkmcnt(8)
	s_waitcnt vmcnt(10)
	s_barrier
	s_waitcnt lgkmcnt(4)
	s_setprio 1
	v_mfma_f32_16x16x32_bf16 v[124:127], v[154:157], v[170:173], v[124:127]
	v_mfma_f32_16x16x32_bf16 v[120:123], v[162:165], v[170:173], v[120:123]
	v_mfma_f32_16x16x32_bf16 v[116:119], v[154:157], v[178:181], v[116:119]
	v_mfma_f32_16x16x32_bf16 v[108:111], v[162:165], v[178:181], v[108:111]
	v_mfma_f32_16x16x32_bf16 v[100:103], v[154:157], v[186:189], v[100:103]
	v_mfma_f32_16x16x32_bf16 v[92:95], v[162:165], v[186:189], v[92:95]
	v_mfma_f32_16x16x32_bf16 v[84:87], v[154:157], v[220:223], v[84:87]
	v_mfma_f32_16x16x32_bf16 v[76:79], v[162:165], v[220:223], v[76:79]
	s_waitcnt lgkmcnt(0)
	v_mfma_f32_16x16x32_bf16 v[124:127], v[158:161], v[174:177], v[124:127]
	v_mfma_f32_16x16x32_bf16 v[120:123], v[166:169], v[174:177], v[120:123]
	v_mfma_f32_16x16x32_bf16 v[116:119], v[158:161], v[182:185], v[116:119]
	v_mfma_f32_16x16x32_bf16 v[108:111], v[166:169], v[182:185], v[108:111]
	v_mfma_f32_16x16x32_bf16 v[100:103], v[158:161], v[216:219], v[100:103]
	v_mfma_f32_16x16x32_bf16 v[92:95], v[166:169], v[216:219], v[92:95]
	v_mfma_f32_16x16x32_bf16 v[84:87], v[158:161], v[224:227], v[84:87]
	v_mfma_f32_16x16x32_bf16 v[76:79], v[166:169], v[224:227], v[76:79]
	s_setprio 0
	s_barrier
	s_add_i32 s37, 0, 0x14000
	v_add_u32_e32 v190, s37, v152
	s_add_i32 s12, s36, s26
	ds_read_b128 v[228:231], v190
	ds_read_b128 v[236:239], v190 offset:2048
	ds_read_b128 v[232:235], v190 offset:1024
	ds_read_b128 v[240:243], v190 offset:3072
	v_lshl_add_u64 v[190:191], s[22:23], 0, v[132:133]
	s_mov_b32 m0, s12
	v_lshl_add_u64 v[244:245], s[22:23], 0, v[128:129]
	global_load_lds_dwordx4 v[190:191], off
	s_add_i32 m0, s12, 0x2000
	s_nop 0
	global_load_lds_dwordx4 v[244:245], off
	s_waitcnt vmcnt(10)
	s_barrier
	s_waitcnt lgkmcnt(2)
	s_setprio 1
	v_mfma_f32_16x16x32_bf16 v[112:115], v[228:231], v[170:173], v[112:115]
	v_mfma_f32_16x16x32_bf16 v[104:107], v[236:239], v[170:173], v[104:107]
	v_mfma_f32_16x16x32_bf16 v[96:99], v[228:231], v[178:181], v[96:99]
	v_mfma_f32_16x16x32_bf16 v[88:91], v[236:239], v[178:181], v[88:91]
	v_mfma_f32_16x16x32_bf16 v[80:83], v[228:231], v[186:189], v[80:83]
	v_mfma_f32_16x16x32_bf16 v[72:75], v[236:239], v[186:189], v[72:75]
	v_mfma_f32_16x16x32_bf16 v[68:71], v[228:231], v[220:223], v[68:71]
	v_mfma_f32_16x16x32_bf16 v[64:67], v[236:239], v[220:223], v[64:67]
	s_waitcnt lgkmcnt(0)
	v_mfma_f32_16x16x32_bf16 v[112:115], v[232:235], v[174:177], v[112:115]
	v_mfma_f32_16x16x32_bf16 v[104:107], v[240:243], v[174:177], v[104:107]
	v_mfma_f32_16x16x32_bf16 v[96:99], v[232:235], v[182:185], v[96:99]
	v_mfma_f32_16x16x32_bf16 v[88:91], v[240:243], v[182:185], v[88:91]
	v_mfma_f32_16x16x32_bf16 v[80:83], v[232:235], v[216:219], v[80:83]
	v_mfma_f32_16x16x32_bf16 v[72:75], v[240:243], v[216:219], v[72:75]
	v_mfma_f32_16x16x32_bf16 v[68:71], v[232:235], v[224:227], v[68:71]
	v_mfma_f32_16x16x32_bf16 v[64:67], v[240:243], v[224:227], v[64:67]
	s_setprio 0
	s_mov_b32 m0, s3
	v_lshl_add_u64 v[246:247], s[18:19], 0, v[132:133]
	s_barrier
	ds_read_b128 v[170:173], v153 offset:16384
	ds_read_b128 v[178:181], v153 offset:18432
	ds_read_b128 v[186:189], v153 offset:20480
	ds_read_b128 v[220:223], v153 offset:22528
	ds_read_b128 v[174:177], v153 offset:17408
	ds_read_b128 v[182:185], v153 offset:19456
	ds_read_b128 v[216:219], v153 offset:21504
	ds_read_b128 v[224:227], v153 offset:23552
	global_load_lds_dwordx4 v[246:247], off
	v_lshl_add_u64 v[248:249], s[18:19], 0, v[128:129]
	s_mov_b32 m0, s5
	s_nop 0
	global_load_lds_dwordx4 v[248:249], off
	s_waitcnt vmcnt(10)
	s_barrier
	s_waitcnt lgkmcnt(4)
	s_setprio 1
	v_mfma_f32_16x16x32_bf16 v[60:63], v[154:157], v[170:173], v[60:63]
	v_mfma_f32_16x16x32_bf16 v[56:59], v[162:165], v[170:173], v[56:59]
	v_mfma_f32_16x16x32_bf16 v[52:55], v[154:157], v[178:181], v[52:55]
	v_mfma_f32_16x16x32_bf16 v[44:47], v[162:165], v[178:181], v[44:47]
	v_mfma_f32_16x16x32_bf16 v[36:39], v[154:157], v[186:189], v[36:39]
	v_mfma_f32_16x16x32_bf16 v[28:31], v[162:165], v[186:189], v[28:31]
	v_mfma_f32_16x16x32_bf16 v[20:23], v[154:157], v[220:223], v[20:23]
	v_mfma_f32_16x16x32_bf16 v[12:15], v[162:165], v[220:223], v[12:15]
	s_waitcnt lgkmcnt(0)
	v_mfma_f32_16x16x32_bf16 v[60:63], v[158:161], v[174:177], v[60:63]
	v_mfma_f32_16x16x32_bf16 v[56:59], v[166:169], v[174:177], v[56:59]
	v_mfma_f32_16x16x32_bf16 v[52:55], v[158:161], v[182:185], v[52:55]
	v_mfma_f32_16x16x32_bf16 v[44:47], v[166:169], v[182:185], v[44:47]
	v_mfma_f32_16x16x32_bf16 v[36:39], v[158:161], v[216:219], v[36:39]
	v_mfma_f32_16x16x32_bf16 v[28:31], v[166:169], v[216:219], v[28:31]
	v_mfma_f32_16x16x32_bf16 v[20:23], v[158:161], v[224:227], v[20:23]
	v_mfma_f32_16x16x32_bf16 v[12:15], v[166:169], v[224:227], v[12:15]
	s_setprio 0
	s_barrier
	s_add_u32 s12, s22, s25
	s_addc_u32 s13, s23, 0
	s_add_i32 s22, s37, s26
	v_lshl_add_u64 v[250:251], s[12:13], 0, v[132:133]
	s_mov_b32 m0, s22
	v_lshl_add_u64 v[252:253], s[12:13], 0, v[128:129]
	global_load_lds_dwordx4 v[250:251], off
	s_add_i32 m0, s22, 0x2000
	s_nop 0
	global_load_lds_dwordx4 v[252:253], off
	v_add_u32_e32 v166, 0x18000, v152
	ds_read_b128 v[154:157], v166
	ds_read_b128 v[158:161], v166 offset:1024
	ds_read_b128 v[162:165], v166 offset:2048
	ds_read_b128 v[166:169], v166 offset:3072
	s_waitcnt vmcnt(10)
	s_barrier
	s_setprio 1
	v_mfma_f32_16x16x32_bf16 v[48:51], v[228:231], v[170:173], v[48:51]
	v_mfma_f32_16x16x32_bf16 v[40:43], v[236:239], v[170:173], v[40:43]
	v_mfma_f32_16x16x32_bf16 v[32:35], v[228:231], v[178:181], v[32:35]
	v_mfma_f32_16x16x32_bf16 v[24:27], v[236:239], v[178:181], v[24:27]
	v_mfma_f32_16x16x32_bf16 v[16:19], v[228:231], v[186:189], v[16:19]
	v_mfma_f32_16x16x32_bf16 v[8:11], v[236:239], v[186:189], v[8:11]
	v_mfma_f32_16x16x32_bf16 v[4:7], v[228:231], v[220:223], v[4:7]
	v_mfma_f32_16x16x32_bf16 v[0:3], v[236:239], v[220:223], v[0:3]
	v_mfma_f32_16x16x32_bf16 v[48:51], v[232:235], v[174:177], v[48:51]
	v_mfma_f32_16x16x32_bf16 v[40:43], v[240:243], v[174:177], v[40:43]
	v_mfma_f32_16x16x32_bf16 v[32:35], v[232:235], v[182:185], v[32:35]
	v_mfma_f32_16x16x32_bf16 v[24:27], v[240:243], v[182:185], v[24:27]
	v_mfma_f32_16x16x32_bf16 v[16:19], v[232:235], v[216:219], v[16:19]
	v_mfma_f32_16x16x32_bf16 v[8:11], v[240:243], v[216:219], v[8:11]
	v_mfma_f32_16x16x32_bf16 v[4:7], v[232:235], v[224:227], v[4:7]
	v_mfma_f32_16x16x32_bf16 v[0:3], v[240:243], v[224:227], v[0:3]
	s_setprio 0
	s_add_i32 s22, 0, 0x18000
	s_barrier
	s_add_u32 s12, s18, s25
	s_addc_u32 s13, s19, 0
	s_mov_b32 m0, s27
	v_lshl_add_u64 v[228:229], s[12:13], 0, v[132:133]
	ds_read_b128 v[170:173], v153 offset:32768
	ds_read_b128 v[178:181], v153 offset:34816
	ds_read_b128 v[186:189], v153 offset:36864
	ds_read_b128 v[220:223], v153 offset:38912
	ds_read_b128 v[174:177], v153 offset:33792
	ds_read_b128 v[182:185], v153 offset:35840
	ds_read_b128 v[216:219], v153 offset:37888
	ds_read_b128 v[224:227], v153 offset:39936
	global_load_lds_dwordx4 v[228:229], off
	v_lshl_add_u64 v[228:229], s[12:13], 0, v[128:129]
	s_mov_b32 m0, s28
	s_nop 0
	global_load_lds_dwordx4 v[228:229], off
	s_waitcnt lgkmcnt(8)
	s_waitcnt vmcnt(10)
	s_barrier
	s_waitcnt lgkmcnt(4)
	s_setprio 1
	v_mfma_f32_16x16x32_bf16 v[124:127], v[154:157], v[170:173], v[124:127]
	v_mfma_f32_16x16x32_bf16 v[120:123], v[162:165], v[170:173], v[120:123]
	v_mfma_f32_16x16x32_bf16 v[116:119], v[154:157], v[178:181], v[116:119]
	v_mfma_f32_16x16x32_bf16 v[108:111], v[162:165], v[178:181], v[108:111]
	v_mfma_f32_16x16x32_bf16 v[100:103], v[154:157], v[186:189], v[100:103]
	v_mfma_f32_16x16x32_bf16 v[92:95], v[162:165], v[186:189], v[92:95]
	v_mfma_f32_16x16x32_bf16 v[84:87], v[154:157], v[220:223], v[84:87]
	v_mfma_f32_16x16x32_bf16 v[76:79], v[162:165], v[220:223], v[76:79]
	s_waitcnt lgkmcnt(0)
	v_mfma_f32_16x16x32_bf16 v[124:127], v[158:161], v[174:177], v[124:127]
	v_mfma_f32_16x16x32_bf16 v[120:123], v[166:169], v[174:177], v[120:123]
	v_mfma_f32_16x16x32_bf16 v[116:119], v[158:161], v[182:185], v[116:119]
	v_mfma_f32_16x16x32_bf16 v[108:111], v[166:169], v[182:185], v[108:111]
	v_mfma_f32_16x16x32_bf16 v[100:103], v[158:161], v[216:219], v[100:103]
	v_mfma_f32_16x16x32_bf16 v[92:95], v[166:169], v[216:219], v[92:95]
	v_mfma_f32_16x16x32_bf16 v[84:87], v[158:161], v[224:227], v[84:87]
	v_mfma_f32_16x16x32_bf16 v[76:79], v[166:169], v[224:227], v[76:79]
	s_setprio 0
	s_barrier
	s_add_i32 s12, 0, 0x1c000
	s_add_i32 s13, s22, s26
	v_add_u32_e32 v200, s12, v152
	v_lshl_add_u64 v[190:191], v[190:191], 0, s[66:67]
	s_mov_b32 m0, s13
	ds_read_b128 v[228:231], v200
	ds_read_b128 v[236:239], v200 offset:2048
	ds_read_b128 v[232:235], v200 offset:1024
	ds_read_b128 v[240:243], v200 offset:3072
	global_load_lds_dwordx4 v[190:191], off
	v_lshl_add_u64 v[190:191], v[244:245], 0, s[66:67]
	s_add_i32 m0, s13, 0x2000
	s_nop 0
	global_load_lds_dwordx4 v[190:191], off
	s_waitcnt vmcnt(10)
	s_barrier
	s_waitcnt lgkmcnt(2)
	s_setprio 1
	v_mfma_f32_16x16x32_bf16 v[112:115], v[228:231], v[170:173], v[112:115]
	v_mfma_f32_16x16x32_bf16 v[104:107], v[236:239], v[170:173], v[104:107]
	v_mfma_f32_16x16x32_bf16 v[96:99], v[228:231], v[178:181], v[96:99]
	v_mfma_f32_16x16x32_bf16 v[88:91], v[236:239], v[178:181], v[88:91]
	v_mfma_f32_16x16x32_bf16 v[80:83], v[228:231], v[186:189], v[80:83]
	v_mfma_f32_16x16x32_bf16 v[72:75], v[236:239], v[186:189], v[72:75]
	v_mfma_f32_16x16x32_bf16 v[68:71], v[228:231], v[220:223], v[68:71]
	v_mfma_f32_16x16x32_bf16 v[64:67], v[236:239], v[220:223], v[64:67]
	s_waitcnt lgkmcnt(0)
	v_mfma_f32_16x16x32_bf16 v[112:115], v[232:235], v[174:177], v[112:115]
	v_mfma_f32_16x16x32_bf16 v[104:107], v[240:243], v[174:177], v[104:107]
	v_mfma_f32_16x16x32_bf16 v[96:99], v[232:235], v[182:185], v[96:99]
	v_mfma_f32_16x16x32_bf16 v[88:91], v[240:243], v[182:185], v[88:91]
	v_mfma_f32_16x16x32_bf16 v[80:83], v[232:235], v[216:219], v[80:83]
	v_mfma_f32_16x16x32_bf16 v[72:75], v[240:243], v[216:219], v[72:75]
	v_mfma_f32_16x16x32_bf16 v[68:71], v[232:235], v[224:227], v[68:71]
	v_mfma_f32_16x16x32_bf16 v[64:67], v[240:243], v[224:227], v[64:67]
	s_setprio 0
	s_mov_b32 m0, s30
	v_lshl_add_u64 v[190:191], v[246:247], 0, s[66:67]
	s_barrier
	ds_read_b128 v[170:173], v153 offset:49152
	ds_read_b128 v[178:181], v153 offset:51200
	ds_read_b128 v[186:189], v153 offset:53248
	ds_read_b128 v[220:223], v153 offset:55296
	ds_read_b128 v[174:177], v153 offset:50176
	ds_read_b128 v[182:185], v153 offset:52224
	ds_read_b128 v[216:219], v153 offset:54272
	ds_read_b128 v[224:227], v153 offset:56320
	global_load_lds_dwordx4 v[190:191], off
	v_lshl_add_u64 v[190:191], v[248:249], 0, s[66:67]
	s_mov_b32 m0, s31
	s_nop 0
	global_load_lds_dwordx4 v[190:191], off
	s_waitcnt vmcnt(10)
	s_barrier
	s_waitcnt lgkmcnt(4)
	s_setprio 1
	v_mfma_f32_16x16x32_bf16 v[60:63], v[154:157], v[170:173], v[60:63]
	v_mfma_f32_16x16x32_bf16 v[56:59], v[162:165], v[170:173], v[56:59]
	v_mfma_f32_16x16x32_bf16 v[52:55], v[154:157], v[178:181], v[52:55]
	v_mfma_f32_16x16x32_bf16 v[44:47], v[162:165], v[178:181], v[44:47]
	v_mfma_f32_16x16x32_bf16 v[36:39], v[154:157], v[186:189], v[36:39]
	v_mfma_f32_16x16x32_bf16 v[28:31], v[162:165], v[186:189], v[28:31]
	v_mfma_f32_16x16x32_bf16 v[20:23], v[154:157], v[220:223], v[20:23]
	v_mfma_f32_16x16x32_bf16 v[12:15], v[162:165], v[220:223], v[12:15]
	s_waitcnt lgkmcnt(0)
	v_mfma_f32_16x16x32_bf16 v[60:63], v[158:161], v[174:177], v[60:63]
	v_mfma_f32_16x16x32_bf16 v[56:59], v[166:169], v[174:177], v[56:59]
	v_mfma_f32_16x16x32_bf16 v[52:55], v[158:161], v[182:185], v[52:55]
	v_mfma_f32_16x16x32_bf16 v[44:47], v[166:169], v[182:185], v[44:47]
	v_mfma_f32_16x16x32_bf16 v[36:39], v[158:161], v[216:219], v[36:39]
	v_mfma_f32_16x16x32_bf16 v[28:31], v[166:169], v[216:219], v[28:31]
	v_mfma_f32_16x16x32_bf16 v[20:23], v[158:161], v[224:227], v[20:23]
	v_mfma_f32_16x16x32_bf16 v[12:15], v[166:169], v[224:227], v[12:15]
	s_setprio 0
	s_barrier
	s_add_i32 s12, s12, s26
	v_lshl_add_u64 v[154:155], v[250:251], 0, s[66:67]
	s_mov_b32 m0, s12
	s_nop 0
	global_load_lds_dwordx4 v[154:155], off
	v_lshl_add_u64 v[154:155], v[252:253], 0, s[66:67]
	s_add_i32 m0, s12, 0x2000
	s_nop 0
	global_load_lds_dwordx4 v[154:155], off
	v_add_u32_e32 v166, 0x10000, v152
	ds_read_b128 v[154:157], v166
	ds_read_b128 v[158:161], v166 offset:1024
	ds_read_b128 v[162:165], v166 offset:2048
	ds_read_b128 v[166:169], v166 offset:3072
	s_waitcnt vmcnt(10)
	s_barrier
	s_setprio 1
	v_mfma_f32_16x16x32_bf16 v[48:51], v[228:231], v[170:173], v[48:51]
	v_mfma_f32_16x16x32_bf16 v[40:43], v[236:239], v[170:173], v[40:43]
	v_mfma_f32_16x16x32_bf16 v[32:35], v[228:231], v[178:181], v[32:35]
	v_mfma_f32_16x16x32_bf16 v[24:27], v[236:239], v[178:181], v[24:27]
	v_mfma_f32_16x16x32_bf16 v[16:19], v[228:231], v[186:189], v[16:19]
	v_mfma_f32_16x16x32_bf16 v[8:11], v[236:239], v[186:189], v[8:11]
	v_mfma_f32_16x16x32_bf16 v[4:7], v[228:231], v[220:223], v[4:7]
	v_mfma_f32_16x16x32_bf16 v[0:3], v[236:239], v[220:223], v[0:3]
	v_mfma_f32_16x16x32_bf16 v[48:51], v[232:235], v[174:177], v[48:51]
	v_mfma_f32_16x16x32_bf16 v[40:43], v[240:243], v[174:177], v[40:43]
	v_mfma_f32_16x16x32_bf16 v[32:35], v[232:235], v[182:185], v[32:35]
	v_mfma_f32_16x16x32_bf16 v[24:27], v[240:243], v[182:185], v[24:27]
	v_mfma_f32_16x16x32_bf16 v[16:19], v[232:235], v[216:219], v[16:19]
	v_mfma_f32_16x16x32_bf16 v[8:11], v[240:243], v[216:219], v[8:11]
	v_mfma_f32_16x16x32_bf16 v[4:7], v[232:235], v[224:227], v[4:7]
	v_mfma_f32_16x16x32_bf16 v[0:3], v[240:243], v[224:227], v[0:3]
	s_setprio 0
	s_cmp_ge_u32 s35, s29
	s_mov_b64 s[12:13], s[16:17]
	s_mov_b32 s18, s35
	s_barrier
	s_cbranch_scc0 .LBB0_70
	s_waitcnt lgkmcnt(0)
	s_and_b64 s[6:7], s[6:7], exec
	v_mov_b32_e32 v128, v135
	s_mov_b64 s[6:7], s[0:1]
	s_load_dwordx2 s[6:7], s[6:7], 0x88
	s_cselect_b32 s3, 0x2000, 0
	v_readfirstlane_b32 s5, v128
	v_lshrrev_b32_e32 v129, 2, v128
	v_cvt_pk_bf16_f32 v104, v104, v105
	s_waitcnt lgkmcnt(0)
	s_add_u32 s6, s6, 0xfea4400
	s_addc_u32 s7, s7, 0
	s_ashr_i32 s8, s5, 2
	s_andn2_b32 s8, s8, 63
	v_and_or_b32 v128, v128, 15, s8
	s_lshr_b32 s5, s5, 1
	v_lshl_add_u32 v150, s2, 8, v128
	s_lshl_b32 s2, s4, s15
	s_and_b32 s5, s5, 0x60
	s_add_i32 s2, s2, s3
	v_and_or_b32 v132, v129, 12, s5
	v_add_u32_e32 v130, s2, v150
	v_mov_b64_e32 v[128:129], s[6:7]
	v_mad_i64_i32 v[130:131], s[4:5], v130, s96, v[128:129]
	s_lshl_b32 s58, s58, 9
	v_lshl_add_u64 v[130:131], v[130:131], 0, s[58:59]
	v_lshlrev_b32_e32 v132, 1, v132
	v_lshl_add_u64 v[130:131], v[130:131], 0, v[132:133]
	v_cvt_pk_bf16_f32 v105, v106, v107
	global_store_dwordx2 v[130:131], v[104:105], off offset:1824
	v_add3_u32 v104, s2, 16, v150
	v_mad_i64_i32 v[104:105], s[4:5], v104, s96, v[128:129]
	v_lshl_add_u64 v[104:105], v[104:105], 0, s[58:59]
	v_lshl_add_u64 v[104:105], v[104:105], 0, v[132:133]
	v_cvt_pk_bf16_f32 v88, v88, v89
	v_cvt_pk_bf16_f32 v89, v90, v91
	global_store_dwordx2 v[104:105], v[88:89], off offset:1824
	v_add3_u32 v88, s2, 32, v150
	v_mad_i64_i32 v[88:89], s[4:5], v88, s96, v[128:129]
	v_lshl_add_u64 v[88:89], v[88:89], 0, s[58:59]
	v_lshl_add_u64 v[88:89], v[88:89], 0, v[132:133]
	v_cvt_pk_bf16_f32 v72, v72, v73
	v_cvt_pk_bf16_f32 v73, v74, v75
	global_store_dwordx2 v[88:89], v[72:73], off offset:1824
	v_add3_u32 v72, s2, 48, v150
	v_mad_i64_i32 v[72:73], s[4:5], v72, s96, v[128:129]
	v_lshl_add_u64 v[72:73], v[72:73], 0, s[58:59]
	v_lshl_add_u64 v[72:73], v[72:73], 0, v[132:133]
	v_cvt_pk_bf16_f32 v64, v64, v65
	s_add_i32 s3, s2, 0x80
	v_cvt_pk_bf16_f32 v65, v66, v67
	global_store_dwordx2 v[72:73], v[64:65], off offset:1824
	v_add_u32_e32 v64, s3, v150
	v_mad_i64_i32 v[64:65], s[4:5], v64, s96, v[128:129]
	v_lshl_add_u64 v[64:65], v[64:65], 0, s[58:59]
	v_lshl_add_u64 v[64:65], v[64:65], 0, v[132:133]
	v_cvt_pk_bf16_f32 v40, v40, v41
	s_add_i32 s3, s2, 0x90
	v_cvt_pk_bf16_f32 v41, v42, v43
	global_store_dwordx2 v[64:65], v[40:41], off offset:1824
	v_add_u32_e32 v40, s3, v150
	v_mad_i64_i32 v[40:41], s[4:5], v40, s96, v[128:129]
	v_lshl_add_u64 v[40:41], v[40:41], 0, s[58:59]
	v_lshl_add_u64 v[40:41], v[40:41], 0, v[132:133]
	v_cvt_pk_bf16_f32 v24, v24, v25
	s_add_i32 s3, s2, 0xa0
	v_cvt_pk_bf16_f32 v25, v26, v27
	global_store_dwordx2 v[40:41], v[24:25], off offset:1824
	v_add_u32_e32 v24, s3, v150
	v_mad_i64_i32 v[24:25], s[4:5], v24, s96, v[128:129]
	v_lshl_add_u64 v[24:25], v[24:25], 0, s[58:59]
	v_lshl_add_u64 v[24:25], v[24:25], 0, v[132:133]
	v_cvt_pk_bf16_f32 v8, v8, v9
	s_addk_i32 s2, 0xb0
	v_cvt_pk_bf16_f32 v9, v10, v11
	global_store_dwordx2 v[24:25], v[8:9], off offset:1824
	v_add_u32_e32 v8, s2, v150
	v_mad_i64_i32 v[8:9], s[2:3], v8, s96, v[128:129]
	v_lshl_add_u64 v[8:9], v[8:9], 0, s[58:59]
	v_cvt_pk_bf16_f32 v106, v116, v117
	v_cvt_pk_bf16_f32 v107, v118, v119
	v_cvt_pk_bf16_f32 v90, v100, v101
	v_cvt_pk_bf16_f32 v91, v102, v103
	v_cvt_pk_bf16_f32 v74, v84, v85
	v_cvt_pk_bf16_f32 v75, v86, v87
	v_cvt_pk_bf16_f32 v42, v52, v53
	v_cvt_pk_bf16_f32 v43, v54, v55
	v_cvt_pk_bf16_f32 v26, v36, v37
	v_cvt_pk_bf16_f32 v27, v38, v39
	v_lshl_add_u64 v[8:9], v[8:9], 0, v[132:133]
	v_cvt_pk_bf16_f32 v10, v20, v21
	v_cvt_pk_bf16_f32 v11, v22, v23
	v_cvt_pk_bf16_f32 v124, v124, v125
	v_cvt_pk_bf16_f32 v125, v126, v127
	global_store_dwordx2 v[130:131], v[124:125], off offset:1536
	v_cvt_pk_bf16_f32 v120, v120, v121
	v_cvt_pk_bf16_f32 v121, v122, v123
	global_store_dwordx2 v[130:131], v[120:121], off offset:1568
	v_cvt_pk_bf16_f32 v112, v112, v113
	v_cvt_pk_bf16_f32 v113, v114, v115
	global_store_dwordx2 v[130:131], v[112:113], off offset:1792
	global_store_dwordx2 v[104:105], v[106:107], off offset:1536
	v_cvt_pk_bf16_f32 v106, v108, v109
	v_cvt_pk_bf16_f32 v107, v110, v111
	global_store_dwordx2 v[104:105], v[106:107], off offset:1568
	v_cvt_pk_bf16_f32 v96, v96, v97
	v_cvt_pk_bf16_f32 v97, v98, v99
	global_store_dwordx2 v[104:105], v[96:97], off offset:1792
	global_store_dwordx2 v[88:89], v[90:91], off offset:1536
	v_cvt_pk_bf16_f32 v90, v92, v93
	v_cvt_pk_bf16_f32 v91, v94, v95
	global_store_dwordx2 v[88:89], v[90:91], off offset:1568
	v_cvt_pk_bf16_f32 v80, v80, v81
	v_cvt_pk_bf16_f32 v81, v82, v83
	global_store_dwordx2 v[88:89], v[80:81], off offset:1792
	global_store_dwordx2 v[72:73], v[74:75], off offset:1536
	v_cvt_pk_bf16_f32 v74, v76, v77
	v_cvt_pk_bf16_f32 v75, v78, v79
	global_store_dwordx2 v[72:73], v[74:75], off offset:1568
	v_cvt_pk_bf16_f32 v68, v68, v69
	v_cvt_pk_bf16_f32 v69, v70, v71
	global_store_dwordx2 v[72:73], v[68:69], off offset:1792
	v_cvt_pk_bf16_f32 v60, v60, v61
	v_cvt_pk_bf16_f32 v61, v62, v63
	global_store_dwordx2 v[64:65], v[60:61], off offset:1536
	v_cvt_pk_bf16_f32 v56, v56, v57
	v_cvt_pk_bf16_f32 v57, v58, v59
	global_store_dwordx2 v[64:65], v[56:57], off offset:1568
	v_cvt_pk_bf16_f32 v48, v48, v49
	v_cvt_pk_bf16_f32 v49, v50, v51
	global_store_dwordx2 v[64:65], v[48:49], off offset:1792
	global_store_dwordx2 v[40:41], v[42:43], off offset:1536
	v_cvt_pk_bf16_f32 v42, v44, v45
	v_cvt_pk_bf16_f32 v43, v46, v47
	global_store_dwordx2 v[40:41], v[42:43], off offset:1568
	v_cvt_pk_bf16_f32 v32, v32, v33
	v_cvt_pk_bf16_f32 v33, v34, v35
	global_store_dwordx2 v[40:41], v[32:33], off offset:1792
	global_store_dwordx2 v[24:25], v[26:27], off offset:1536
	v_cvt_pk_bf16_f32 v26, v28, v29
	v_cvt_pk_bf16_f32 v27, v30, v31
	global_store_dwordx2 v[24:25], v[26:27], off offset:1568
	v_cvt_pk_bf16_f32 v16, v16, v17
	v_cvt_pk_bf16_f32 v17, v18, v19
	global_store_dwordx2 v[24:25], v[16:17], off offset:1792
	global_store_dwordx2 v[8:9], v[10:11], off offset:1536
	v_cvt_pk_bf16_f32 v10, v12, v13
	v_cvt_pk_bf16_f32 v11, v14, v15
	global_store_dwordx2 v[8:9], v[10:11], off offset:1568
	v_cvt_pk_bf16_f32 v4, v4, v5
	v_cvt_pk_bf16_f32 v5, v6, v7
	global_store_dwordx2 v[8:9], v[4:5], off offset:1792
	v_cvt_pk_bf16_f32 v0, v0, v1
	v_cvt_pk_bf16_f32 v1, v2, v3
	global_store_dwordx2 v[8:9], v[0:1], off offset:1824
	s_waitcnt vmcnt(0)
	s_cmpk_lt_u32 s14, 0x100
	s_cbranch_scc0 .LBB0_73
	s_barrier

.LBB0_137:
	s_andn2_b64 vcc, exec, s[2:3]
	s_cbranch_vccnz .LBB0_1033
	v_bfe_i32 v1, v5, 27, 1
	v_lshlrev_b32_e32 v3, 4, v5
	v_lshrrev_b32_e32 v1, 22, v1
	v_add_u32_e32 v1, v3, v1
	v_and_b32_e32 v1, 0xfffffc00, v1
	v_sub_u32_e32 v1, v3, v1
	v_lshrrev_b32_e32 v2, 4, v1
	v_bitop3_b32 v2, v2, v1, 32 bitop3:0x6c
	v_ashrrev_i32_e32 v1, 31, v1
	v_lshrrev_b32_e32 v1, 26, v1
	v_ashrrev_i32_e32 v0, 31, v5
	v_add_u32_e32 v1, v2, v1
	v_lshrrev_b32_e32 v0, 26, v0
	v_ashrrev_i32_e32 v1, 6, v1
	v_add_u32_e32 v0, v5, v0
	v_mul_i32_i24_e32 v7, 64, v1
	v_ashrrev_i32_e32 v0, 6, v0
	v_sub_u32_e32 v2, v2, v7
	v_lshlrev_b32_e32 v4, 3, v0
	v_lshlrev_b32_e32 v6, 5, v0
	v_ashrrev_i16_sdwa v2, v205, sext(v2) dst_sel:DWORD dst_unused:UNUSED_PAD src0_sel:DWORD src1_sel:BYTE_0
	v_and_b32_e32 v4, 0x1ffff0, v4
	v_and_b32_e32 v6, 32, v6
	v_bfe_i32 v2, v2, 0, 16
	v_add_u32_e32 v6, v6, v2
	v_add_lshl_u32 v4, v1, v4, 11
	v_lshl_add_u32 v150, v6, 1, v4
	v_add_u32_e32 v4, 0x2000, v3
	v_ashrrev_i32_e32 v3, 31, v4
	v_lshrrev_b32_e32 v3, 22, v3
	v_add_u32_e32 v3, v4, v3
	v_ashrrev_i32_e32 v3, 10, v3
	v_mul_i32_i24_e32 v6, 0x400, v3
	s_add_u32 s86, s80, 0x62a4400
	v_sub_u32_e32 v4, v4, v6
	v_writelane_b32 v254, s82, 51
	s_addc_u32 s87, s81, 0
	s_mul_i32 s3, s40, 0x580000
	v_lshrrev_b32_e32 v6, 4, v4
	v_writelane_b32 v254, s83, 52
	s_mul_hi_u32 s2, s40, 0x580000
	s_add_u32 s3, s80, s3
	v_bitop3_b32 v6, v6, v4, 32 bitop3:0x6c
	v_lshlrev_b32_e32 v4, 3, v3
	v_writelane_b32 v254, s80, 61
	s_addc_u32 s2, s81, s2
	v_and_b32_e32 v7, 0x1ffff0, v4
	v_ashrrev_i32_e32 v4, 31, v6
	v_writelane_b32 v254, s81, 62
	s_add_u32 s41, s3, 0x4200000
	v_lshrrev_b32_e32 v4, 26, v4
	s_addc_u32 s14, s2, 0
	s_ashr_i32 s4, s9, 8
	s_waitcnt vmcnt(1)
	v_add_u32_e32 v8, v6, v4
	v_writelane_b32 v254, s9, 53
	s_ashr_i32 s5, s9, 6
	s_ashr_i32 s9, s8, 31
	s_cmp_eq_u32 s26, 5
	s_cselect_b32 s27, 7, s26
	s_cmp_eq_u32 s26, 7
	s_cselect_b32 s26, 5, s27
	s_ashr_i32 s27, s26, 31
	v_ashrrev_i32_e32 v4, 6, v8
	v_and_b32_e32 v8, 0xc0, v8
	s_lshl_b32 s15, s5, 10
	s_lshl_b64 s[2:3], s[8:9], 19
	s_lshl_b64 s[6:7], s[26:27], 19
	v_sub_u32_e32 v6, v6, v8
	s_add_u32 s6, s41, s6
	v_lshlrev_b32_e32 v9, 5, v3
	v_ashrrev_i16_sdwa v6, v205, sext(v6) dst_sel:DWORD dst_unused:UNUSED_PAD src0_sel:DWORD src1_sel:BYTE_0
	s_addc_u32 s7, s14, s7
	s_add_i32 s50, s15, 0
	v_and_b32_e32 v9, 32, v9
	v_bfe_i32 v6, v6, 0, 16
	s_add_i32 m0, s50, 0x10000
	v_add_u32_e32 v8, v9, v6
	v_add_lshl_u32 v7, v4, v7, 11
	global_load_lds_dwordx4 v150, s[6:7]
	s_add_i32 m0, s50, 0x12000
	v_lshl_add_u32 v152, v8, 1, v7
	s_add_u32 s2, s86, s2
	global_load_lds_dwordx4 v152, s[6:7]
	s_addc_u32 s3, s87, s3
	s_mov_b32 m0, s50
	s_add_i32 s51, s50, 0x2000
	global_load_lds_dwordx4 v150, s[2:3]
	s_mov_b32 m0, s51
	s_add_u32 s10, s6, 0x40000
	global_load_lds_dwordx4 v152, s[2:3]
	s_addc_u32 s11, s7, 0
	s_add_i32 m0, s50, 0x14000
	v_mov_b32_e32 v203, 0x1000
	global_load_lds_dwordx4 v150, s[10:11]
	s_add_i32 m0, s50, 0x16000
	s_nop 0
	global_load_lds_dwordx4 v152, s[10:11]
	s_add_u32 s10, s2, 0x40000
	s_addc_u32 s11, s3, 0
	s_add_i32 s36, s50, 0x4000
	s_mov_b32 m0, s36
	s_add_i32 s37, s50, 0x6000
	global_load_lds_dwordx4 v150, s[10:11]
	s_mov_b32 m0, s37
	s_cmp_lg_u32 s4, 1
	global_load_lds_dwordx4 v152, s[10:11]
	s_cbranch_scc1 .LBB0_140
	s_barrier

.LBB0_144:
	s_ashr_i32 s19, s18, 31
	v_cmp_lt_i64_e32 vcc, s[10:11], v[140:141]
	s_lshl_b64 s[10:11], s[18:19], 19
	s_add_u32 s22, s86, s10
	s_addc_u32 s23, s87, s11
	s_and_b64 s[10:11], vcc, exec
	s_cselect_b32 s9, s23, s3
	s_cselect_b32 s12, s22, s2
	s_cmp_eq_u32 s16, 5
	s_cselect_b32 s17, 7, s16
	s_cmp_eq_u32 s16, 7
	s_cselect_b32 s16, 5, s17
	s_ashr_i32 s17, s16, 31
	s_lshl_b64 s[10:11], s[16:17], 19
	s_add_u32 s24, s41, s10
	s_addc_u32 s25, s14, s11
	s_and_b64 s[10:11], vcc, exec
	s_cselect_b32 s13, s25, s7
	s_cselect_b32 s17, s24, s6
	s_add_u32 s2, s2, 0x40080
	s_addc_u32 s3, s3, 0
	s_add_u32 s19, s6, 0x100
	v_mov_b32_e32 v0, 0
	s_addc_u32 s27, s7, 0
	s_waitcnt lgkmcnt(0)
	s_mov_b32 s28, -2
	v_mov_b32_e32 v1, v0
	v_mov_b64_e32 v[2:3], 0
	v_mov_b64_e32 v[4:5], 0
	v_mov_b64_e32 v[6:7], 0
	v_mov_b64_e32 v[8:9], 0
	v_mov_b64_e32 v[10:11], 0
	v_mov_b64_e32 v[12:13], 0
	v_mov_b64_e32 v[14:15], 0
	v_mov_b64_e32 v[16:17], 0
	v_mov_b64_e32 v[18:19], 0
	v_mov_b64_e32 v[20:21], 0
	v_mov_b64_e32 v[22:23], 0
	v_mov_b64_e32 v[24:25], 0
	v_mov_b64_e32 v[26:27], 0
	v_mov_b64_e32 v[28:29], 0
	v_mov_b64_e32 v[30:31], 0
	v_mov_b64_e32 v[32:33], 0
	v_mov_b64_e32 v[34:35], 0
	v_mov_b64_e32 v[36:37], 0
	v_mov_b64_e32 v[38:39], 0
	v_mov_b64_e32 v[40:41], 0
	v_mov_b64_e32 v[42:43], 0
	v_mov_b64_e32 v[44:45], 0
	v_mov_b64_e32 v[46:47], 0
	v_mov_b64_e32 v[48:49], 0
	v_mov_b64_e32 v[50:51], 0
	v_mov_b64_e32 v[52:53], 0
	v_mov_b64_e32 v[54:55], 0
	v_mov_b64_e32 v[56:57], 0
	v_mov_b64_e32 v[58:59], 0
	v_mov_b64_e32 v[60:61], 0
	v_mov_b64_e32 v[62:63], 0
	v_mov_b64_e32 v[64:65], 0
	v_mov_b64_e32 v[66:67], 0
	v_mov_b64_e32 v[68:69], 0
	v_mov_b64_e32 v[70:71], 0
	v_mov_b64_e32 v[72:73], 0
	v_mov_b64_e32 v[74:75], 0
	v_mov_b64_e32 v[76:77], 0
	v_mov_b64_e32 v[78:79], 0
	v_mov_b64_e32 v[80:81], 0
	v_mov_b64_e32 v[82:83], 0
	v_mov_b64_e32 v[84:85], 0
	v_mov_b64_e32 v[86:87], 0
	v_mov_b64_e32 v[88:89], 0
	v_mov_b64_e32 v[90:91], 0
	v_mov_b64_e32 v[92:93], 0
	v_mov_b64_e32 v[94:95], 0
	v_mov_b64_e32 v[96:97], 0
	v_mov_b64_e32 v[98:99], 0
	v_mov_b64_e32 v[100:101], 0
	v_mov_b64_e32 v[102:103], 0
	v_mov_b64_e32 v[104:105], 0
	v_mov_b64_e32 v[106:107], 0
	v_mov_b64_e32 v[108:109], 0
	v_mov_b64_e32 v[110:111], 0
	v_mov_b64_e32 v[112:113], 0
	v_mov_b64_e32 v[114:115], 0
	v_mov_b64_e32 v[116:117], 0
	v_mov_b64_e32 v[118:119], 0
	v_mov_b64_e32 v[120:121], 0
	v_mov_b64_e32 v[122:123], 0
	v_mov_b64_e32 v[124:125], 0
	v_mov_b64_e32 v[126:127], 0
	v_add_u32_e32 v166, 0x10000, v215
	ds_read_b128 v[128:131], v166
	ds_read_b128 v[158:161], v166 offset:1024
	ds_read_b128 v[162:165], v166 offset:2048
	ds_read_b128 v[166:169], v166 offset:3072
.LBB0_145:
	s_add_u32 s6, s2, 0xfffc0080
	s_addc_u32 s7, s3, -1
	s_add_i32 s29, 0, 0x10000
	s_cmp_eq_u32 s28, 12
	s_cselect_b32 s11, s9, s7
	s_cselect_b32 s10, s12, s6
	s_cselect_b32 s7, s13, s27
	s_cselect_b32 s6, s17, s19
	v_lshl_add_u64 v[190:191], s[2:3], 0, v[154:155]
	s_add_i32 m0, s50, 0xc000
	ds_read_b128 v[170:173], v216
	ds_read_b128 v[178:181], v216 offset:2048
	ds_read_b128 v[186:189], v216 offset:4096
	ds_read_b128 v[222:225], v216 offset:6144
	ds_read_b128 v[174:177], v216 offset:1024
	ds_read_b128 v[182:185], v216 offset:3072
	ds_read_b128 v[218:221], v216 offset:5120
	ds_read_b128 v[226:229], v216 offset:7168
	global_load_lds_dwordx4 v[190:191], off
	v_lshl_add_u64 v[190:191], s[2:3], 0, v[156:157]
	s_add_i32 m0, s50, 0xe000
	s_nop 0
	global_load_lds_dwordx4 v[190:191], off
	s_waitcnt lgkmcnt(8)
	s_waitcnt vmcnt(10)
	s_barrier
	s_waitcnt lgkmcnt(4)
	s_setprio 1
	v_mfma_f32_16x16x32_bf16 v[124:127], v[128:131], v[170:173], v[124:127]
	v_mfma_f32_16x16x32_bf16 v[120:123], v[162:165], v[170:173], v[120:123]
	v_mfma_f32_16x16x32_bf16 v[108:111], v[128:131], v[178:181], v[108:111]
	v_mfma_f32_16x16x32_bf16 v[104:107], v[162:165], v[178:181], v[104:107]
	v_mfma_f32_16x16x32_bf16 v[92:95], v[128:131], v[186:189], v[92:95]
	v_mfma_f32_16x16x32_bf16 v[88:91], v[162:165], v[186:189], v[88:91]
	v_mfma_f32_16x16x32_bf16 v[76:79], v[128:131], v[222:225], v[76:79]
	v_mfma_f32_16x16x32_bf16 v[72:75], v[162:165], v[222:225], v[72:75]
	s_waitcnt lgkmcnt(0)
	v_mfma_f32_16x16x32_bf16 v[124:127], v[158:161], v[174:177], v[124:127]
	v_mfma_f32_16x16x32_bf16 v[120:123], v[166:169], v[174:177], v[120:123]
	v_mfma_f32_16x16x32_bf16 v[108:111], v[158:161], v[182:185], v[108:111]
	v_mfma_f32_16x16x32_bf16 v[104:107], v[166:169], v[182:185], v[104:107]
	v_mfma_f32_16x16x32_bf16 v[92:95], v[158:161], v[218:221], v[92:95]
	v_mfma_f32_16x16x32_bf16 v[88:91], v[166:169], v[218:221], v[88:91]
	v_mfma_f32_16x16x32_bf16 v[76:79], v[158:161], v[226:229], v[76:79]
	v_mfma_f32_16x16x32_bf16 v[72:75], v[166:169], v[226:229], v[72:75]
	s_setprio 0
	s_barrier
	s_add_i32 s34, 0, 0x14000
	s_add_i32 s29, s29, s15
	v_add_u32_e32 v132, s34, v215
	v_lshl_add_u64 v[190:191], s[6:7], 0, v[150:151]
	s_mov_b32 m0, s29
	ds_read_b128 v[230:233], v132
	ds_read_b128 v[238:241], v132 offset:2048
	ds_read_b128 v[234:237], v132 offset:1024
	ds_read_b128 v[242:245], v132 offset:3072
	global_load_lds_dwordx4 v[190:191], off
	v_lshl_add_u64 v[246:247], s[6:7], 0, v[152:153]
	s_add_i32 m0, s29, 0x2000
	s_nop 0
	global_load_lds_dwordx4 v[246:247], off
	s_waitcnt vmcnt(10)
	s_barrier
	s_waitcnt lgkmcnt(2)
	s_setprio 1
	v_mfma_f32_16x16x32_bf16 v[116:119], v[230:233], v[170:173], v[116:119]
	v_mfma_f32_16x16x32_bf16 v[112:115], v[238:241], v[170:173], v[112:115]
	v_mfma_f32_16x16x32_bf16 v[100:103], v[230:233], v[178:181], v[100:103]
	v_mfma_f32_16x16x32_bf16 v[96:99], v[238:241], v[178:181], v[96:99]
	v_mfma_f32_16x16x32_bf16 v[84:87], v[230:233], v[186:189], v[84:87]
	v_mfma_f32_16x16x32_bf16 v[80:83], v[238:241], v[186:189], v[80:83]
	v_mfma_f32_16x16x32_bf16 v[68:71], v[230:233], v[222:225], v[68:71]
	v_mfma_f32_16x16x32_bf16 v[64:67], v[238:241], v[222:225], v[64:67]
	s_waitcnt lgkmcnt(0)
	v_mfma_f32_16x16x32_bf16 v[116:119], v[234:237], v[174:177], v[116:119]
	v_mfma_f32_16x16x32_bf16 v[112:115], v[242:245], v[174:177], v[112:115]
	v_mfma_f32_16x16x32_bf16 v[100:103], v[234:237], v[182:185], v[100:103]
	v_mfma_f32_16x16x32_bf16 v[96:99], v[242:245], v[182:185], v[96:99]
	v_mfma_f32_16x16x32_bf16 v[84:87], v[234:237], v[218:221], v[84:87]
	v_mfma_f32_16x16x32_bf16 v[80:83], v[242:245], v[218:221], v[80:83]
	v_mfma_f32_16x16x32_bf16 v[68:71], v[234:237], v[226:229], v[68:71]
	v_mfma_f32_16x16x32_bf16 v[64:67], v[242:245], v[226:229], v[64:67]
	s_setprio 0
	s_mov_b32 m0, s50
	v_lshl_add_u64 v[248:249], s[10:11], 0, v[150:151]
	s_barrier
	ds_read_b128 v[170:173], v216 offset:16384
	ds_read_b128 v[178:181], v216 offset:18432
	ds_read_b128 v[186:189], v216 offset:20480
	ds_read_b128 v[222:225], v216 offset:22528
	ds_read_b128 v[174:177], v216 offset:17408
	ds_read_b128 v[182:185], v216 offset:19456
	ds_read_b128 v[218:221], v216 offset:21504
	ds_read_b128 v[226:229], v216 offset:23552
	global_load_lds_dwordx4 v[248:249], off
	v_lshl_add_u64 v[250:251], s[10:11], 0, v[152:153]
	s_mov_b32 m0, s51
	s_nop 0
	global_load_lds_dwordx4 v[250:251], off
	s_waitcnt vmcnt(10)
	s_barrier
	s_waitcnt lgkmcnt(4)
	s_setprio 1
	v_mfma_f32_16x16x32_bf16 v[60:63], v[128:131], v[170:173], v[60:63]
	v_mfma_f32_16x16x32_bf16 v[56:59], v[162:165], v[170:173], v[56:59]
	v_mfma_f32_16x16x32_bf16 v[44:47], v[128:131], v[178:181], v[44:47]
	v_mfma_f32_16x16x32_bf16 v[40:43], v[162:165], v[178:181], v[40:43]
	v_mfma_f32_16x16x32_bf16 v[28:31], v[128:131], v[186:189], v[28:31]
	v_mfma_f32_16x16x32_bf16 v[24:27], v[162:165], v[186:189], v[24:27]
	v_mfma_f32_16x16x32_bf16 v[12:15], v[128:131], v[222:225], v[12:15]
	v_mfma_f32_16x16x32_bf16 v[8:11], v[162:165], v[222:225], v[8:11]
	s_waitcnt lgkmcnt(0)
	v_mfma_f32_16x16x32_bf16 v[60:63], v[158:161], v[174:177], v[60:63]
	v_mfma_f32_16x16x32_bf16 v[56:59], v[166:169], v[174:177], v[56:59]
	v_mfma_f32_16x16x32_bf16 v[44:47], v[158:161], v[182:185], v[44:47]
	v_mfma_f32_16x16x32_bf16 v[40:43], v[166:169], v[182:185], v[40:43]
	v_mfma_f32_16x16x32_bf16 v[28:31], v[158:161], v[218:221], v[28:31]
	v_mfma_f32_16x16x32_bf16 v[24:27], v[166:169], v[218:221], v[24:27]
	v_mfma_f32_16x16x32_bf16 v[12:15], v[158:161], v[226:229], v[12:15]
	v_mfma_f32_16x16x32_bf16 v[8:11], v[166:169], v[226:229], v[8:11]
	s_setprio 0
	s_barrier
	s_add_u32 s30, s6, 0x40000
	s_addc_u32 s31, s7, 0
	s_add_i32 s29, s34, s15
	v_lshl_add_u64 v[128:129], s[30:31], 0, v[150:151]
	s_mov_b32 m0, s29
	s_nop 0
	global_load_lds_dwordx4 v[128:129], off
	v_lshl_add_u64 v[128:129], s[30:31], 0, v[152:153]
	s_add_i32 m0, s29, 0x2000
	s_nop 0
	global_load_lds_dwordx4 v[128:129], off
	v_add_u32_e32 v166, 0x18000, v215
	ds_read_b128 v[128:131], v166
	ds_read_b128 v[158:161], v166 offset:1024
	ds_read_b128 v[162:165], v166 offset:2048
	ds_read_b128 v[166:169], v166 offset:3072
	s_waitcnt vmcnt(10)
	s_barrier
	s_setprio 1
	v_mfma_f32_16x16x32_bf16 v[52:55], v[230:233], v[170:173], v[52:55]
	v_mfma_f32_16x16x32_bf16 v[48:51], v[238:241], v[170:173], v[48:51]
	v_mfma_f32_16x16x32_bf16 v[36:39], v[230:233], v[178:181], v[36:39]
	v_mfma_f32_16x16x32_bf16 v[32:35], v[238:241], v[178:181], v[32:35]
	v_mfma_f32_16x16x32_bf16 v[20:23], v[230:233], v[186:189], v[20:23]
	v_mfma_f32_16x16x32_bf16 v[16:19], v[238:241], v[186:189], v[16:19]
	v_mfma_f32_16x16x32_bf16 v[4:7], v[230:233], v[222:225], v[4:7]
	v_mfma_f32_16x16x32_bf16 v[0:3], v[238:241], v[222:225], v[0:3]
	v_mfma_f32_16x16x32_bf16 v[52:55], v[234:237], v[174:177], v[52:55]
	v_mfma_f32_16x16x32_bf16 v[48:51], v[242:245], v[174:177], v[48:51]
	v_mfma_f32_16x16x32_bf16 v[36:39], v[234:237], v[182:185], v[36:39]
	v_mfma_f32_16x16x32_bf16 v[32:35], v[242:245], v[182:185], v[32:35]
	v_mfma_f32_16x16x32_bf16 v[20:23], v[234:237], v[218:221], v[20:23]
	v_mfma_f32_16x16x32_bf16 v[16:19], v[242:245], v[218:221], v[16:19]
	v_mfma_f32_16x16x32_bf16 v[4:7], v[234:237], v[226:229], v[4:7]
	v_mfma_f32_16x16x32_bf16 v[0:3], v[242:245], v[226:229], v[0:3]
	s_setprio 0
	s_add_i32 s29, 0, 0x18000
	s_barrier
	s_add_u32 s10, s10, 0x40000
	s_addc_u32 s11, s11, 0
	s_mov_b32 m0, s36
	v_lshl_add_u64 v[230:231], s[10:11], 0, v[150:151]
	ds_read_b128 v[170:173], v216 offset:32768
	ds_read_b128 v[178:181], v216 offset:34816
	ds_read_b128 v[186:189], v216 offset:36864
	ds_read_b128 v[222:225], v216 offset:38912
	ds_read_b128 v[174:177], v216 offset:33792
	ds_read_b128 v[182:185], v216 offset:35840
	ds_read_b128 v[218:221], v216 offset:37888
	ds_read_b128 v[226:229], v216 offset:39936
	global_load_lds_dwordx4 v[230:231], off
	v_lshl_add_u64 v[230:231], s[10:11], 0, v[152:153]
	s_mov_b32 m0, s37
	s_nop 0
	global_load_lds_dwordx4 v[230:231], off
	s_waitcnt lgkmcnt(8)
	s_waitcnt vmcnt(10)
	s_barrier
	s_waitcnt lgkmcnt(4)
	s_setprio 1
	v_mfma_f32_16x16x32_bf16 v[124:127], v[128:131], v[170:173], v[124:127]
	v_mfma_f32_16x16x32_bf16 v[120:123], v[162:165], v[170:173], v[120:123]
	v_mfma_f32_16x16x32_bf16 v[108:111], v[128:131], v[178:181], v[108:111]
	v_mfma_f32_16x16x32_bf16 v[104:107], v[162:165], v[178:181], v[104:107]
	v_mfma_f32_16x16x32_bf16 v[92:95], v[128:131], v[186:189], v[92:95]
	v_mfma_f32_16x16x32_bf16 v[88:91], v[162:165], v[186:189], v[88:91]
	v_mfma_f32_16x16x32_bf16 v[76:79], v[128:131], v[222:225], v[76:79]
	v_mfma_f32_16x16x32_bf16 v[72:75], v[162:165], v[222:225], v[72:75]
	s_waitcnt lgkmcnt(0)
	v_mfma_f32_16x16x32_bf16 v[124:127], v[158:161], v[174:177], v[124:127]
	v_mfma_f32_16x16x32_bf16 v[120:123], v[166:169], v[174:177], v[120:123]
	v_mfma_f32_16x16x32_bf16 v[108:111], v[158:161], v[182:185], v[108:111]
	v_mfma_f32_16x16x32_bf16 v[104:107], v[166:169], v[182:185], v[104:107]
	v_mfma_f32_16x16x32_bf16 v[92:95], v[158:161], v[218:221], v[92:95]
	v_mfma_f32_16x16x32_bf16 v[88:91], v[166:169], v[218:221], v[88:91]
	v_mfma_f32_16x16x32_bf16 v[76:79], v[158:161], v[226:229], v[76:79]
	v_mfma_f32_16x16x32_bf16 v[72:75], v[166:169], v[226:229], v[72:75]
	s_setprio 0
	s_barrier
	s_add_i32 s10, 0, 0x1c000
	s_add_i32 s11, s29, s15
	v_add_u32_e32 v132, s10, v215
	v_lshl_add_u64 v[190:191], v[190:191], 0, s[66:67]
	s_mov_b32 m0, s11
	ds_read_b128 v[230:233], v132
	ds_read_b128 v[238:241], v132 offset:2048
	ds_read_b128 v[234:237], v132 offset:1024
	ds_read_b128 v[242:245], v132 offset:3072
	global_load_lds_dwordx4 v[190:191], off
	v_lshl_add_u64 v[190:191], v[246:247], 0, s[66:67]
	s_add_i32 m0, s11, 0x2000
	s_nop 0
	global_load_lds_dwordx4 v[190:191], off
	s_waitcnt vmcnt(10)
	s_barrier
	s_waitcnt lgkmcnt(2)
	s_setprio 1
	v_mfma_f32_16x16x32_bf16 v[116:119], v[230:233], v[170:173], v[116:119]
	v_mfma_f32_16x16x32_bf16 v[112:115], v[238:241], v[170:173], v[112:115]
	v_mfma_f32_16x16x32_bf16 v[100:103], v[230:233], v[178:181], v[100:103]
	v_mfma_f32_16x16x32_bf16 v[96:99], v[238:241], v[178:181], v[96:99]
	v_mfma_f32_16x16x32_bf16 v[84:87], v[230:233], v[186:189], v[84:87]
	v_mfma_f32_16x16x32_bf16 v[80:83], v[238:241], v[186:189], v[80:83]
	v_mfma_f32_16x16x32_bf16 v[68:71], v[230:233], v[222:225], v[68:71]
	v_mfma_f32_16x16x32_bf16 v[64:67], v[238:241], v[222:225], v[64:67]
	s_waitcnt lgkmcnt(0)
	v_mfma_f32_16x16x32_bf16 v[116:119], v[234:237], v[174:177], v[116:119]
	v_mfma_f32_16x16x32_bf16 v[112:115], v[242:245], v[174:177], v[112:115]
	v_mfma_f32_16x16x32_bf16 v[100:103], v[234:237], v[182:185], v[100:103]
	v_mfma_f32_16x16x32_bf16 v[96:99], v[242:245], v[182:185], v[96:99]
	v_mfma_f32_16x16x32_bf16 v[84:87], v[234:237], v[218:221], v[84:87]
	v_mfma_f32_16x16x32_bf16 v[80:83], v[242:245], v[218:221], v[80:83]
	v_mfma_f32_16x16x32_bf16 v[68:71], v[234:237], v[226:229], v[68:71]
	v_mfma_f32_16x16x32_bf16 v[64:67], v[242:245], v[226:229], v[64:67]
	s_setprio 0
	s_mov_b32 m0, s52
	v_lshl_add_u64 v[190:191], v[248:249], 0, s[66:67]
	s_barrier
	ds_read_b128 v[170:173], v216 offset:49152
	ds_read_b128 v[178:181], v216 offset:51200
	ds_read_b128 v[186:189], v216 offset:53248
	ds_read_b128 v[222:225], v216 offset:55296
	ds_read_b128 v[174:177], v216 offset:50176
	ds_read_b128 v[182:185], v216 offset:52224
	ds_read_b128 v[218:221], v216 offset:54272
	ds_read_b128 v[226:229], v216 offset:56320
	global_load_lds_dwordx4 v[190:191], off
	v_lshl_add_u64 v[190:191], v[250:251], 0, s[66:67]
	s_mov_b32 m0, s53
	s_nop 0
	global_load_lds_dwordx4 v[190:191], off
	s_waitcnt vmcnt(10)
	s_barrier
	s_waitcnt lgkmcnt(4)
	s_setprio 1
	v_mfma_f32_16x16x32_bf16 v[60:63], v[128:131], v[170:173], v[60:63]
	v_mfma_f32_16x16x32_bf16 v[56:59], v[162:165], v[170:173], v[56:59]
	v_mfma_f32_16x16x32_bf16 v[44:47], v[128:131], v[178:181], v[44:47]
	v_mfma_f32_16x16x32_bf16 v[40:43], v[162:165], v[178:181], v[40:43]
	v_mfma_f32_16x16x32_bf16 v[28:31], v[128:131], v[186:189], v[28:31]
	v_mfma_f32_16x16x32_bf16 v[24:27], v[162:165], v[186:189], v[24:27]
	v_mfma_f32_16x16x32_bf16 v[12:15], v[128:131], v[222:225], v[12:15]
	v_mfma_f32_16x16x32_bf16 v[8:11], v[162:165], v[222:225], v[8:11]
	s_waitcnt lgkmcnt(0)
	v_mfma_f32_16x16x32_bf16 v[60:63], v[158:161], v[174:177], v[60:63]
	v_mfma_f32_16x16x32_bf16 v[56:59], v[166:169], v[174:177], v[56:59]
	v_mfma_f32_16x16x32_bf16 v[44:47], v[158:161], v[182:185], v[44:47]
	v_mfma_f32_16x16x32_bf16 v[40:43], v[166:169], v[182:185], v[40:43]
	v_mfma_f32_16x16x32_bf16 v[28:31], v[158:161], v[218:221], v[28:31]
	v_mfma_f32_16x16x32_bf16 v[24:27], v[166:169], v[218:221], v[24:27]
	v_mfma_f32_16x16x32_bf16 v[12:15], v[158:161], v[226:229], v[12:15]
	v_mfma_f32_16x16x32_bf16 v[8:11], v[166:169], v[226:229], v[8:11]
	s_setprio 0
	s_barrier
	s_add_u32 s6, s6, 0x40080
	s_addc_u32 s7, s7, 0
	s_add_i32 s10, s10, s15
	v_lshl_add_u64 v[128:129], s[6:7], 0, v[150:151]
	s_mov_b32 m0, s10
	s_nop 0
	global_load_lds_dwordx4 v[128:129], off
	v_lshl_add_u64 v[128:129], s[6:7], 0, v[152:153]
	s_add_i32 m0, s10, 0x2000
	s_nop 0
	global_load_lds_dwordx4 v[128:129], off
	v_add_u32_e32 v166, 0x10000, v215
	ds_read_b128 v[128:131], v166
	ds_read_b128 v[158:161], v166 offset:1024
	ds_read_b128 v[162:165], v166 offset:2048
	ds_read_b128 v[166:169], v166 offset:3072
	s_waitcnt vmcnt(10)
	s_barrier
	s_setprio 1
	v_mfma_f32_16x16x32_bf16 v[52:55], v[230:233], v[170:173], v[52:55]
	v_mfma_f32_16x16x32_bf16 v[48:51], v[238:241], v[170:173], v[48:51]
	v_mfma_f32_16x16x32_bf16 v[36:39], v[230:233], v[178:181], v[36:39]
	v_mfma_f32_16x16x32_bf16 v[32:35], v[238:241], v[178:181], v[32:35]
	v_mfma_f32_16x16x32_bf16 v[20:23], v[230:233], v[186:189], v[20:23]
	v_mfma_f32_16x16x32_bf16 v[16:19], v[238:241], v[186:189], v[16:19]
	v_mfma_f32_16x16x32_bf16 v[4:7], v[230:233], v[222:225], v[4:7]
	v_mfma_f32_16x16x32_bf16 v[0:3], v[238:241], v[222:225], v[0:3]
	v_mfma_f32_16x16x32_bf16 v[52:55], v[234:237], v[174:177], v[52:55]
	v_mfma_f32_16x16x32_bf16 v[48:51], v[242:245], v[174:177], v[48:51]
	v_mfma_f32_16x16x32_bf16 v[36:39], v[234:237], v[182:185], v[36:39]
	v_mfma_f32_16x16x32_bf16 v[32:35], v[242:245], v[182:185], v[32:35]
	v_mfma_f32_16x16x32_bf16 v[20:23], v[234:237], v[218:221], v[20:23]
	v_mfma_f32_16x16x32_bf16 v[16:19], v[242:245], v[218:221], v[16:19]
	v_mfma_f32_16x16x32_bf16 v[4:7], v[234:237], v[226:229], v[4:7]
	v_mfma_f32_16x16x32_bf16 v[0:3], v[242:245], v[226:229], v[0:3]
	s_setprio 0
	s_add_i32 s28, s28, 2
	s_add_u32 s2, s2, 0x100
	s_addc_u32 s3, s3, 0
	s_add_u32 s19, s19, 0x100
	s_addc_u32 s27, s27, 0
	s_cmp_gt_u32 s28, 13
	s_barrier
	s_cbranch_scc0 .LBB0_145
	s_waitcnt lgkmcnt(0)
	v_mov_b32_e32 v166, v135
	s_mov_b64 s[2:3], s[0:1]
	v_readfirstlane_b32 s27, v166
	s_bfe_u32 s19, s27, 0x20006
	s_load_dwordx2 s[30:31], s[2:3], 0x88
	s_mov_b64 s[2:3], s[0:1]
	s_cmp_gt_i32 s8, 31
	s_load_dwordx2 s[28:29], s[2:3], 0x80
	s_cselect_b64 s[6:7], -1, 0
	s_cmp_lt_i32 s8, 32
	s_cselect_b64 s[2:3], -1, 0
	s_ashr_i32 s9, s27, 2
	s_lshl_b32 s8, s8, 8
	s_and_b32 s17, s9, 0xffffffc0
	v_and_b32_e32 v217, 15, v166
	s_add_i32 s17, s17, s8
	v_bfe_u32 v186, v166, 4, 2
	v_or_b32_e32 v158, s17, v217
	s_cmp_gt_i32 s26, 3
	s_mov_b64 s[8:9], -1
	s_cbranch_scc0 .LBB0_829
	s_cmp_gt_u32 s26, 5
	s_cbranch_scc0 .LBB0_409
	s_cmp_gt_u32 s26, 8
	s_cbranch_scc0 .LBB0_406
	v_and_b32_e32 v128, 1, v166
	v_cmp_eq_u32_e64 s[8:9], 0, v128
	v_cmp_eq_u32_e32 vcc, 1, v128
	v_cvt_pk_bf16_f32 v128, v124, v125
	v_cvt_pk_bf16_f32 v132, v126, v127
	s_nop 0
	v_cndmask_b32_e64 v129, v128, v132, s[8:9]
	s_nop 1
	v_mov_b32_dpp v129, v129 quad_perm:[1,0,3,2] row_mask:0xf bank_mask:0xf bound_ctrl:1
	s_mov_b32 s10, 0x05040100
	s_mov_b32 s11, 0x07060302
	v_cndmask_b32_e32 v128, v128, v129, vcc
	v_cndmask_b32_e32 v132, v129, v132, vcc
	v_perm_b32 v130, v132, v128, s10
	v_perm_b32 v131, v132, v128, s11
	s_add_i32 s58, s26, -9
	s_and_b64 s[10:11], s[6:7], exec
	s_movk_i32 s10, 0x100
	s_cselect_b32 s12, 0x800, s10
	s_lshl_b64 s[10:11], s[58:59], 22
	s_lshl_b32 s58, s12, 1
	v_lshlrev_b32_e32 v128, 2, v186
	s_add_i32 s12, s58, -1
	v_lshl_or_b32 v159, s19, 5, v128
	v_mov_b32_e32 v128, s12
	s_add_i32 s12, s17, 0xffffe000
	s_lshr_b32 s34, s17, 8
	s_ashr_i32 s35, s12, 11
	s_and_b64 s[12:13], s[6:7], exec
	s_cselect_b32 s12, s35, s34
	s_movk_i32 s13, 0x7ff
	s_cselect_b32 s34, s13, 0xff
	s_lshl_b32 s38, s12, 8
	s_and_b64 s[12:13], s[6:7], exec
	s_mov_b32 s12, 0xeea4400
	s_cselect_b32 s12, s12, 0xf6a4400
	s_cselect_b32 s35, 12, 9
	s_waitcnt lgkmcnt(0)
	s_add_u32 s12, s30, s12
	s_addc_u32 s13, s31, 0
	v_cndmask_b32_e64 v132, v128, 0, s[8:9]
	v_and_b32_e32 v160, s34, v158
	v_or_b32_e32 v128, s38, v159
	s_add_u32 s10, s12, s10
	v_ashrrev_i32_e32 v129, 31, v128
	s_addc_u32 s11, s13, s11
	v_lshlrev_b32_e32 v160, 1, v160
	v_mov_b32_e32 v161, v133
	v_lshl_add_u64 v[164:165], s[10:11], 0, v[160:161]
	v_lshlrev_b64 v[128:129], s35, v[128:129]
	v_lshl_add_u64 v[160:161], v[164:165], 0, v[128:129]
	v_lshl_add_u64 v[160:161], v[132:133], 1, v[160:161]
	global_store_dword v[160:161], v130, off
	v_lshl_add_u64 v[160:161], v[160:161], 0, s[58:59]
	global_store_dword v[160:161], v131, off
	v_cvt_pk_bf16_f32 v130, v120, v121
	v_cvt_pk_bf16_f32 v161, v122, v123
	s_nop 0
	v_cndmask_b32_e64 v131, v130, v161, s[8:9]
	s_nop 1
	v_mov_b32_dpp v131, v131 quad_perm:[1,0,3,2] row_mask:0xf bank_mask:0xf bound_ctrl:1
	s_mov_b32 s12, 0x05040100
	s_mov_b32 s13, 0x07060302
	v_cndmask_b32_e32 v130, v130, v131, vcc
	v_cndmask_b32_e32 v161, v131, v161, vcc
	v_perm_b32 v160, v161, v130, s12
	v_perm_b32 v162, v161, v130, s13
	v_or_b32_e32 v167, 16, v159
	v_or_b32_e32 v130, s38, v167
	v_ashrrev_i32_e32 v131, 31, v130
	v_lshlrev_b64 v[130:131], s35, v[130:131]
	v_lshl_add_u64 v[168:169], v[164:165], 0, v[130:131]
	v_lshl_add_u64 v[168:169], v[132:133], 1, v[168:169]
	global_store_dword v[168:169], v160, off
	v_lshl_add_u64 v[160:161], v[168:169], 0, s[58:59]
	global_store_dword v[160:161], v162, off
	v_cvt_pk_bf16_f32 v160, v116, v117
	v_cvt_pk_bf16_f32 v163, v118, v119
	s_nop 0
	v_cndmask_b32_e64 v161, v160, v163, s[8:9]
	s_nop 1
	v_mov_b32_dpp v161, v161 quad_perm:[1,0,3,2] row_mask:0xf bank_mask:0xf bound_ctrl:1
	s_mov_b32 s12, 0x05040100
	s_mov_b32 s13, 0x07060302
	v_cndmask_b32_e32 v160, v160, v161, vcc
	v_cndmask_b32_e32 v163, v161, v163, vcc
	v_perm_b32 v162, v163, v160, s12
	v_perm_b32 v169, v163, v160, s13
	v_or_b32_e32 v168, 0x80, v159
	v_or_b32_e32 v160, s38, v168
	v_ashrrev_i32_e32 v161, 31, v160
	v_lshlrev_b64 v[160:161], s35, v[160:161]
	v_lshl_add_u64 v[170:171], v[164:165], 0, v[160:161]
	v_lshl_add_u64 v[170:171], v[132:133], 1, v[170:171]
	global_store_dword v[170:171], v162, off
	v_lshl_add_u64 v[162:163], v[170:171], 0, s[58:59]
	global_store_dword v[162:163], v169, off
	v_cvt_pk_bf16_f32 v162, v112, v113
	v_cvt_pk_bf16_f32 v169, v114, v115
	s_nop 0
	v_cndmask_b32_e64 v163, v162, v169, s[8:9]
	s_nop 1
	v_mov_b32_dpp v163, v163 quad_perm:[1,0,3,2] row_mask:0xf bank_mask:0xf bound_ctrl:1
	s_mov_b32 s12, 0x05040100
	s_mov_b32 s13, 0x07060302
	v_cndmask_b32_e32 v162, v162, v163, vcc
	v_cndmask_b32_e32 v169, v163, v169, vcc
	v_perm_b32 v170, v169, v162, s12
	v_perm_b32 v171, v169, v162, s13
	v_or_b32_e32 v169, 0x90, v159
	v_or_b32_e32 v162, s38, v169
	v_ashrrev_i32_e32 v163, 31, v162
	v_lshlrev_b64 v[162:163], s35, v[162:163]
	v_lshl_add_u64 v[164:165], v[164:165], 0, v[162:163]
	v_lshl_add_u64 v[164:165], v[132:133], 1, v[164:165]
	global_store_dword v[164:165], v170, off
	v_lshl_add_u64 v[164:165], v[164:165], 0, s[58:59]
	global_store_dword v[164:165], v171, off
	v_cvt_pk_bf16_f32 v164, v108, v109
	v_cvt_pk_bf16_f32 v171, v110, v111
	s_nop 0
	v_cndmask_b32_e64 v165, v164, v171, s[8:9]
	s_nop 1
	v_mov_b32_dpp v165, v165 quad_perm:[1,0,3,2] row_mask:0xf bank_mask:0xf bound_ctrl:1
	s_mov_b32 s12, 0x05040100
	s_mov_b32 s13, 0x07060302
	v_cndmask_b32_e32 v164, v164, v165, vcc
	v_cndmask_b32_e32 v171, v165, v171, vcc
	v_perm_b32 v170, v171, v164, s12
	v_perm_b32 v172, v171, v164, s13
	v_bitop3_b32 v164, v158, s34, 16 bitop3:0xc8
	v_lshlrev_b32_e32 v164, 1, v164
	v_mov_b32_e32 v165, v133
	v_lshl_add_u64 v[164:165], s[10:11], 0, v[164:165]
	v_lshl_add_u64 v[174:175], v[164:165], 0, v[128:129]
	v_lshl_add_u64 v[174:175], v[132:133], 1, v[174:175]
	global_store_dword v[174:175], v170, off
	v_lshl_add_u64 v[170:171], v[174:175], 0, s[58:59]
	global_store_dword v[170:171], v172, off
	v_cvt_pk_bf16_f32 v171, v104, v105
	v_cvt_pk_bf16_f32 v173, v106, v107
	s_nop 0
	v_cndmask_b32_e64 v170, v171, v173, s[8:9]
	s_nop 1
	v_mov_b32_dpp v172, v170 quad_perm:[1,0,3,2] row_mask:0xf bank_mask:0xf bound_ctrl:1
	s_mov_b32 s12, 0x05040100
	s_mov_b32 s13, 0x07060302
	v_cndmask_b32_e32 v171, v171, v172, vcc
	v_cndmask_b32_e32 v173, v172, v173, vcc
	v_perm_b32 v170, v173, v171, s12
	v_perm_b32 v174, v173, v171, s13
	v_lshl_add_u64 v[172:173], v[164:165], 0, v[130:131]
	v_lshl_add_u64 v[172:173], v[132:133], 1, v[172:173]
	global_store_dword v[172:173], v170, off
	v_lshl_add_u64 v[170:171], v[172:173], 0, s[58:59]
	global_store_dword v[170:171], v174, off
	v_cvt_pk_bf16_f32 v171, v100, v101
	v_cvt_pk_bf16_f32 v173, v102, v103
	s_nop 0
	v_cndmask_b32_e64 v170, v171, v173, s[8:9]
	s_nop 1
	v_mov_b32_dpp v172, v170 quad_perm:[1,0,3,2] row_mask:0xf bank_mask:0xf bound_ctrl:1
	s_mov_b32 s12, 0x05040100
	s_mov_b32 s13, 0x07060302
	v_cndmask_b32_e32 v171, v171, v172, vcc
	v_cndmask_b32_e32 v173, v172, v173, vcc
	v_perm_b32 v170, v173, v171, s12
	v_perm_b32 v174, v173, v171, s13
	v_lshl_add_u64 v[172:173], v[164:165], 0, v[160:161]
	v_lshl_add_u64 v[172:173], v[132:133], 1, v[172:173]
	global_store_dword v[172:173], v170, off
	v_lshl_add_u64 v[170:171], v[172:173], 0, s[58:59]
	global_store_dword v[170:171], v174, off
	v_cvt_pk_bf16_f32 v171, v96, v97
	v_cvt_pk_bf16_f32 v173, v98, v99
	s_nop 0
	v_cndmask_b32_e64 v170, v171, v173, s[8:9]
	s_nop 1
	v_mov_b32_dpp v172, v170 quad_perm:[1,0,3,2] row_mask:0xf bank_mask:0xf bound_ctrl:1
	s_mov_b32 s12, 0x05040100
	s_mov_b32 s13, 0x07060302
	v_cndmask_b32_e32 v171, v171, v172, vcc
	v_cndmask_b32_e32 v173, v172, v173, vcc
	v_perm_b32 v170, v173, v171, s12
	v_perm_b32 v174, v173, v171, s13
	v_lshl_add_u64 v[164:165], v[164:165], 0, v[162:163]
	v_lshl_add_u64 v[164:165], v[132:133], 1, v[164:165]
	global_store_dword v[164:165], v170, off
	v_lshl_add_u64 v[164:165], v[164:165], 0, s[58:59]
	global_store_dword v[164:165], v174, off
	v_cvt_pk_bf16_f32 v164, v92, v93
	v_cvt_pk_bf16_f32 v171, v94, v95
	s_nop 0
	v_cndmask_b32_e64 v165, v164, v171, s[8:9]
	s_nop 1
	v_mov_b32_dpp v165, v165 quad_perm:[1,0,3,2] row_mask:0xf bank_mask:0xf bound_ctrl:1
	s_mov_b32 s12, 0x05040100
	s_mov_b32 s13, 0x07060302
	v_cndmask_b32_e32 v164, v164, v165, vcc
	v_cndmask_b32_e32 v171, v165, v171, vcc
	v_perm_b32 v170, v171, v164, s12
	v_perm_b32 v172, v171, v164, s13
	v_bitop3_b32 v164, v158, s34, 32 bitop3:0xc8
	v_lshlrev_b32_e32 v164, 1, v164
	v_mov_b32_e32 v165, v133
	v_lshl_add_u64 v[164:165], s[10:11], 0, v[164:165]
	v_lshl_add_u64 v[174:175], v[164:165], 0, v[128:129]
	v_lshl_add_u64 v[174:175], v[132:133], 1, v[174:175]
	global_store_dword v[174:175], v170, off
	v_lshl_add_u64 v[170:171], v[174:175], 0, s[58:59]
	global_store_dword v[170:171], v172, off
	v_cvt_pk_bf16_f32 v171, v88, v89
	v_cvt_pk_bf16_f32 v173, v90, v91
	s_nop 0
	v_cndmask_b32_e64 v170, v171, v173, s[8:9]
	s_nop 1
	v_mov_b32_dpp v172, v170 quad_perm:[1,0,3,2] row_mask:0xf bank_mask:0xf bound_ctrl:1
	s_mov_b32 s12, 0x05040100
	s_mov_b32 s13, 0x07060302
	v_cndmask_b32_e32 v171, v171, v172, vcc
	v_cndmask_b32_e32 v173, v172, v173, vcc
	v_perm_b32 v170, v173, v171, s12
	v_perm_b32 v174, v173, v171, s13
	v_lshl_add_u64 v[172:173], v[164:165], 0, v[130:131]
	v_lshl_add_u64 v[172:173], v[132:133], 1, v[172:173]
	global_store_dword v[172:173], v170, off
	v_lshl_add_u64 v[170:171], v[172:173], 0, s[58:59]
	global_store_dword v[170:171], v174, off
	v_cvt_pk_bf16_f32 v171, v84, v85
	v_cvt_pk_bf16_f32 v173, v86, v87
	s_nop 0
	v_cndmask_b32_e64 v170, v171, v173, s[8:9]
	s_nop 1
	v_mov_b32_dpp v172, v170 quad_perm:[1,0,3,2] row_mask:0xf bank_mask:0xf bound_ctrl:1
	s_mov_b32 s12, 0x05040100
	s_mov_b32 s13, 0x07060302
	v_cndmask_b32_e32 v171, v171, v172, vcc
	v_cndmask_b32_e32 v173, v172, v173, vcc
	v_perm_b32 v170, v173, v171, s12
	v_perm_b32 v174, v173, v171, s13
	v_lshl_add_u64 v[172:173], v[164:165], 0, v[160:161]
	v_lshl_add_u64 v[172:173], v[132:133], 1, v[172:173]
	global_store_dword v[172:173], v170, off
	v_lshl_add_u64 v[170:171], v[172:173], 0, s[58:59]
	global_store_dword v[170:171], v174, off
	v_cvt_pk_bf16_f32 v171, v80, v81
	v_cvt_pk_bf16_f32 v173, v82, v83
	s_nop 0
	v_cndmask_b32_e64 v170, v171, v173, s[8:9]
	s_nop 1
	v_mov_b32_dpp v172, v170 quad_perm:[1,0,3,2] row_mask:0xf bank_mask:0xf bound_ctrl:1
	s_mov_b32 s12, 0x05040100
	s_mov_b32 s13, 0x07060302
	v_cndmask_b32_e32 v171, v171, v172, vcc
	v_cndmask_b32_e32 v173, v172, v173, vcc
	v_perm_b32 v170, v173, v171, s12
	v_perm_b32 v174, v173, v171, s13
	v_lshl_add_u64 v[164:165], v[164:165], 0, v[162:163]
	v_lshl_add_u64 v[164:165], v[132:133], 1, v[164:165]
	global_store_dword v[164:165], v170, off
	v_lshl_add_u64 v[164:165], v[164:165], 0, s[58:59]
	global_store_dword v[164:165], v174, off
	v_cvt_pk_bf16_f32 v164, v76, v77
	v_cvt_pk_bf16_f32 v171, v78, v79
	s_nop 0
	v_cndmask_b32_e64 v165, v164, v171, s[8:9]
	s_nop 1
	v_mov_b32_dpp v165, v165 quad_perm:[1,0,3,2] row_mask:0xf bank_mask:0xf bound_ctrl:1
	s_mov_b32 s12, 0x05040100
	s_mov_b32 s13, 0x07060302
	v_cndmask_b32_e32 v164, v164, v165, vcc
	v_cndmask_b32_e32 v171, v165, v171, vcc
	v_perm_b32 v170, v171, v164, s12
	v_perm_b32 v172, v171, v164, s13
	v_bitop3_b32 v164, v158, s34, 48 bitop3:0xc8
	v_lshlrev_b32_e32 v164, 1, v164
	v_mov_b32_e32 v165, v133
	v_lshl_add_u64 v[164:165], s[10:11], 0, v[164:165]
	v_lshl_add_u64 v[128:129], v[164:165], 0, v[128:129]
	v_lshl_add_u64 v[128:129], v[132:133], 1, v[128:129]
	global_store_dword v[128:129], v170, off
	v_lshl_add_u64 v[128:129], v[128:129], 0, s[58:59]
	global_store_dword v[128:129], v172, off
	v_cvt_pk_bf16_f32 v129, v72, v73
	v_cvt_pk_bf16_f32 v171, v74, v75
	s_nop 0
	v_cndmask_b32_e64 v128, v129, v171, s[8:9]
	s_nop 1
	v_mov_b32_dpp v170, v128 quad_perm:[1,0,3,2] row_mask:0xf bank_mask:0xf bound_ctrl:1
	s_mov_b32 s12, 0x05040100
	s_mov_b32 s13, 0x07060302
	v_cndmask_b32_e32 v129, v129, v170, vcc
	v_cndmask_b32_e32 v171, v170, v171, vcc
	v_perm_b32 v128, v171, v129, s12
	v_perm_b32 v172, v171, v129, s13
	v_lshl_add_u64 v[130:131], v[164:165], 0, v[130:131]
	v_lshl_add_u64 v[130:131], v[132:133], 1, v[130:131]
	global_store_dword v[130:131], v128, off
	v_lshl_add_u64 v[128:129], v[130:131], 0, s[58:59]
	global_store_dword v[128:129], v172, off
	v_cvt_pk_bf16_f32 v129, v68, v69
	v_cvt_pk_bf16_f32 v131, v70, v71
	s_nop 0
	v_cndmask_b32_e64 v128, v129, v131, s[8:9]
	s_nop 1
	v_mov_b32_dpp v130, v128 quad_perm:[1,0,3,2] row_mask:0xf bank_mask:0xf bound_ctrl:1
	s_mov_b32 s12, 0x05040100
	s_mov_b32 s13, 0x07060302
	v_cndmask_b32_e32 v129, v129, v130, vcc
	v_cndmask_b32_e32 v131, v130, v131, vcc
	v_perm_b32 v128, v131, v129, s12
	v_perm_b32 v170, v131, v129, s13
	v_lshl_add_u64 v[130:131], v[164:165], 0, v[160:161]
	v_lshl_add_u64 v[130:131], v[132:133], 1, v[130:131]
	global_store_dword v[130:131], v128, off
	v_lshl_add_u64 v[128:129], v[130:131], 0, s[58:59]
	global_store_dword v[128:129], v170, off
	v_cvt_pk_bf16_f32 v129, v64, v65
	v_cvt_pk_bf16_f32 v131, v66, v67
	s_nop 0
	v_cndmask_b32_e64 v128, v129, v131, s[8:9]
	s_nop 1
	v_mov_b32_dpp v130, v128 quad_perm:[1,0,3,2] row_mask:0xf bank_mask:0xf bound_ctrl:1
	s_mov_b32 s12, 0x05040100
	s_mov_b32 s13, 0x07060302
	v_cndmask_b32_e32 v129, v129, v130, vcc
	v_cndmask_b32_e32 v131, v130, v131, vcc
	v_perm_b32 v128, v131, v129, s12
	v_perm_b32 v160, v131, v129, s13
	v_lshl_add_u64 v[130:131], v[164:165], 0, v[162:163]
	v_lshl_add_u64 v[130:131], v[132:133], 1, v[130:131]
	global_store_dword v[130:131], v128, off
	v_lshl_add_u64 v[128:129], v[130:131], 0, s[58:59]
	global_store_dword v[128:129], v160, off
	v_cvt_pk_bf16_f32 v128, v60, v61
	v_cvt_pk_bf16_f32 v160, v62, v63
	s_nop 0
	v_cndmask_b32_e64 v129, v128, v160, s[8:9]
	s_nop 1
	v_mov_b32_dpp v129, v129 quad_perm:[1,0,3,2] row_mask:0xf bank_mask:0xf bound_ctrl:1
	s_mov_b32 s12, 0x05040100
	s_mov_b32 s13, 0x07060302
	v_cndmask_b32_e32 v128, v128, v129, vcc
	v_cndmask_b32_e32 v160, v129, v160, vcc
	v_perm_b32 v130, v160, v128, s12
	v_perm_b32 v131, v160, v128, s13
	s_add_i32 s12, s17, 0xffffe080
	v_add_u32_e32 v128, 0x80, v158
	s_ashr_i32 s12, s12, 11
	v_lshrrev_b32_e32 v129, 8, v128
	v_mov_b32_e32 v160, s12
	v_cndmask_b32_e64 v129, v129, v160, s[6:7]
	v_lshlrev_b32_e32 v162, 8, v129
	v_and_b32_e32 v160, s34, v128
	v_or_b32_e32 v128, v162, v159
	v_ashrrev_i32_e32 v129, 31, v128
	v_lshlrev_b32_e32 v160, 1, v160
	v_mov_b32_e32 v161, v133
	v_lshl_add_u64 v[164:165], s[10:11], 0, v[160:161]
	v_lshlrev_b64 v[128:129], s35, v[128:129]
	v_lshl_add_u64 v[160:161], v[164:165], 0, v[128:129]
	v_lshl_add_u64 v[160:161], v[132:133], 1, v[160:161]
	global_store_dword v[160:161], v130, off
	v_lshl_add_u64 v[160:161], v[160:161], 0, s[58:59]
	global_store_dword v[160:161], v131, off
	v_cvt_pk_bf16_f32 v130, v56, v57
	v_cvt_pk_bf16_f32 v160, v58, v59
	s_nop 0
	v_cndmask_b32_e64 v131, v130, v160, s[8:9]
	s_nop 1
	v_mov_b32_dpp v131, v131 quad_perm:[1,0,3,2] row_mask:0xf bank_mask:0xf bound_ctrl:1
	s_mov_b32 s12, 0x05040100
	s_mov_b32 s13, 0x07060302
	v_cndmask_b32_e32 v130, v130, v131, vcc
	v_cndmask_b32_e32 v160, v131, v160, vcc
	v_perm_b32 v159, v160, v130, s12
	v_perm_b32 v161, v160, v130, s13
	v_or_b32_e32 v130, v162, v167
	v_ashrrev_i32_e32 v131, 31, v130
	v_lshlrev_b64 v[130:131], s35, v[130:131]
	v_lshl_add_u64 v[170:171], v[164:165], 0, v[130:131]
	v_lshl_add_u64 v[170:171], v[132:133], 1, v[170:171]
	global_store_dword v[170:171], v159, off
	v_lshl_add_u64 v[170:171], v[170:171], 0, s[58:59]
	v_cvt_pk_bf16_f32 v160, v52, v53
	v_cvt_pk_bf16_f32 v163, v54, v55
	global_store_dword v[170:171], v161, off
	v_cndmask_b32_e64 v159, v160, v163, s[8:9]
	s_nop 1
	v_mov_b32_dpp v161, v159 quad_perm:[1,0,3,2] row_mask:0xf bank_mask:0xf bound_ctrl:1
	s_mov_b32 s12, 0x05040100
	s_mov_b32 s13, 0x07060302
	v_cndmask_b32_e32 v160, v160, v161, vcc
	v_cndmask_b32_e32 v163, v161, v163, vcc
	v_perm_b32 v159, v163, v160, s12
	v_perm_b32 v167, v163, v160, s13
	v_or_b32_e32 v160, v162, v168
	v_ashrrev_i32_e32 v161, 31, v160
	v_lshlrev_b64 v[160:161], s35, v[160:161]
	v_lshl_add_u64 v[170:171], v[164:165], 0, v[160:161]
	v_lshl_add_u64 v[170:171], v[132:133], 1, v[170:171]
	global_store_dword v[170:171], v159, off
	v_lshl_add_u64 v[170:171], v[170:171], 0, s[58:59]
	v_cvt_pk_bf16_f32 v163, v48, v49
	v_cvt_pk_bf16_f32 v168, v50, v51
	global_store_dword v[170:171], v167, off
	v_cndmask_b32_e64 v159, v163, v168, s[8:9]
	s_nop 1
	v_mov_b32_dpp v167, v159 quad_perm:[1,0,3,2] row_mask:0xf bank_mask:0xf bound_ctrl:1
	s_mov_b32 s12, 0x05040100
	s_mov_b32 s13, 0x07060302
	v_cndmask_b32_e32 v163, v163, v167, vcc
	v_cndmask_b32_e32 v168, v167, v168, vcc
	v_perm_b32 v159, v168, v163, s12
	v_perm_b32 v170, v168, v163, s13
	v_or_b32_e32 v162, v162, v169
	v_ashrrev_i32_e32 v163, 31, v162
	v_lshlrev_b64 v[162:163], s35, v[162:163]
	v_lshl_add_u64 v[164:165], v[164:165], 0, v[162:163]
	v_lshl_add_u64 v[164:165], v[132:133], 1, v[164:165]
	global_store_dword v[164:165], v159, off
	v_lshl_add_u64 v[164:165], v[164:165], 0, s[58:59]
	global_store_dword v[164:165], v170, off
	v_cvt_pk_bf16_f32 v164, v44, v45
	v_cvt_pk_bf16_f32 v167, v46, v47
	s_nop 0
	v_cndmask_b32_e64 v159, v164, v167, s[8:9]
	s_nop 1
	v_mov_b32_dpp v165, v159 quad_perm:[1,0,3,2] row_mask:0xf bank_mask:0xf bound_ctrl:1
	s_mov_b32 s12, 0x05040100
	s_mov_b32 s13, 0x07060302
	v_cndmask_b32_e32 v164, v164, v165, vcc
	v_cndmask_b32_e32 v167, v165, v167, vcc
	v_perm_b32 v159, v167, v164, s12
	v_perm_b32 v168, v167, v164, s13
	v_add_u32_e32 v164, 0x90, v158
	v_and_b32_e32 v164, s34, v164
	v_lshlrev_b32_e32 v164, 1, v164
	v_mov_b32_e32 v165, v133
	v_lshl_add_u64 v[164:165], s[10:11], 0, v[164:165]
	v_lshl_add_u64 v[170:171], v[164:165], 0, v[128:129]
	v_lshl_add_u64 v[170:171], v[132:133], 1, v[170:171]
	global_store_dword v[170:171], v159, off
	v_lshl_add_u64 v[170:171], v[170:171], 0, s[58:59]
	v_cvt_pk_bf16_f32 v167, v40, v41
	v_cvt_pk_bf16_f32 v169, v42, v43
	global_store_dword v[170:171], v168, off
	v_cndmask_b32_e64 v159, v167, v169, s[8:9]
	s_nop 1
	v_mov_b32_dpp v168, v159 quad_perm:[1,0,3,2] row_mask:0xf bank_mask:0xf bound_ctrl:1
	s_mov_b32 s12, 0x05040100
	s_mov_b32 s13, 0x07060302
	v_cndmask_b32_e32 v167, v167, v168, vcc
	v_cndmask_b32_e32 v169, v168, v169, vcc
	v_perm_b32 v159, v169, v167, s12
	v_perm_b32 v170, v169, v167, s13
	v_lshl_add_u64 v[168:169], v[164:165], 0, v[130:131]
	v_lshl_add_u64 v[168:169], v[132:133], 1, v[168:169]
	global_store_dword v[168:169], v159, off
	v_lshl_add_u64 v[168:169], v[168:169], 0, s[58:59]
	global_store_dword v[168:169], v170, off
	v_cvt_pk_bf16_f32 v167, v36, v37
	v_cvt_pk_bf16_f32 v169, v38, v39
	s_nop 0
	v_cndmask_b32_e64 v159, v167, v169, s[8:9]
	s_nop 1
	v_mov_b32_dpp v168, v159 quad_perm:[1,0,3,2] row_mask:0xf bank_mask:0xf bound_ctrl:1
	s_mov_b32 s12, 0x05040100
	s_mov_b32 s13, 0x07060302
	v_cndmask_b32_e32 v167, v167, v168, vcc
	v_cndmask_b32_e32 v169, v168, v169, vcc
	v_perm_b32 v159, v169, v167, s12
	v_perm_b32 v170, v169, v167, s13
	v_lshl_add_u64 v[168:169], v[164:165], 0, v[160:161]
	v_lshl_add_u64 v[168:169], v[132:133], 1, v[168:169]
	global_store_dword v[168:169], v159, off
	v_lshl_add_u64 v[168:169], v[168:169], 0, s[58:59]
	global_store_dword v[168:169], v170, off
	v_cvt_pk_bf16_f32 v167, v32, v33
	v_cvt_pk_bf16_f32 v169, v34, v35
	s_nop 0
	v_cndmask_b32_e64 v159, v167, v169, s[8:9]
	s_nop 1
	v_mov_b32_dpp v168, v159 quad_perm:[1,0,3,2] row_mask:0xf bank_mask:0xf bound_ctrl:1
	s_mov_b32 s12, 0x05040100
	s_mov_b32 s13, 0x07060302
	v_cndmask_b32_e32 v167, v167, v168, vcc
	v_cndmask_b32_e32 v169, v168, v169, vcc
	v_perm_b32 v159, v169, v167, s12
	v_perm_b32 v170, v169, v167, s13
	v_lshl_add_u64 v[164:165], v[164:165], 0, v[162:163]
	v_lshl_add_u64 v[164:165], v[132:133], 1, v[164:165]
	global_store_dword v[164:165], v159, off
	v_lshl_add_u64 v[164:165], v[164:165], 0, s[58:59]
	global_store_dword v[164:165], v170, off
	v_cvt_pk_bf16_f32 v164, v28, v29
	v_cvt_pk_bf16_f32 v167, v30, v31
	s_nop 0
	v_cndmask_b32_e64 v159, v164, v167, s[8:9]
	s_nop 1
	v_mov_b32_dpp v165, v159 quad_perm:[1,0,3,2] row_mask:0xf bank_mask:0xf bound_ctrl:1
	s_mov_b32 s12, 0x05040100
	s_mov_b32 s13, 0x07060302
	v_cndmask_b32_e32 v164, v164, v165, vcc
	v_cndmask_b32_e32 v167, v165, v167, vcc
	v_perm_b32 v159, v167, v164, s12
	v_perm_b32 v168, v167, v164, s13
	v_add_u32_e32 v164, 0xa0, v158
	v_and_b32_e32 v164, s34, v164
	v_lshlrev_b32_e32 v164, 1, v164
	v_mov_b32_e32 v165, v133
	v_lshl_add_u64 v[164:165], s[10:11], 0, v[164:165]
	v_lshl_add_u64 v[170:171], v[164:165], 0, v[128:129]
	v_lshl_add_u64 v[170:171], v[132:133], 1, v[170:171]
	global_store_dword v[170:171], v159, off
	v_lshl_add_u64 v[170:171], v[170:171], 0, s[58:59]
	v_cvt_pk_bf16_f32 v167, v24, v25
	v_cvt_pk_bf16_f32 v169, v26, v27
	global_store_dword v[170:171], v168, off
	v_cndmask_b32_e64 v159, v167, v169, s[8:9]
	s_nop 1
	v_mov_b32_dpp v168, v159 quad_perm:[1,0,3,2] row_mask:0xf bank_mask:0xf bound_ctrl:1
	s_mov_b32 s12, 0x05040100
	s_mov_b32 s13, 0x07060302
	v_cndmask_b32_e32 v167, v167, v168, vcc
	v_cndmask_b32_e32 v169, v168, v169, vcc
	v_perm_b32 v159, v169, v167, s12
	v_perm_b32 v170, v169, v167, s13
	v_lshl_add_u64 v[168:169], v[164:165], 0, v[130:131]
	v_lshl_add_u64 v[168:169], v[132:133], 1, v[168:169]
	global_store_dword v[168:169], v159, off
	v_lshl_add_u64 v[168:169], v[168:169], 0, s[58:59]
	global_store_dword v[168:169], v170, off
	v_cvt_pk_bf16_f32 v167, v20, v21
	v_cvt_pk_bf16_f32 v169, v22, v23
	s_nop 0
	v_cndmask_b32_e64 v159, v167, v169, s[8:9]
	s_nop 1
	v_mov_b32_dpp v168, v159 quad_perm:[1,0,3,2] row_mask:0xf bank_mask:0xf bound_ctrl:1
	s_mov_b32 s12, 0x05040100
	s_mov_b32 s13, 0x07060302
	v_cndmask_b32_e32 v167, v167, v168, vcc
	v_cndmask_b32_e32 v169, v168, v169, vcc
	v_perm_b32 v159, v169, v167, s12
	v_perm_b32 v170, v169, v167, s13
	v_lshl_add_u64 v[168:169], v[164:165], 0, v[160:161]
	v_lshl_add_u64 v[168:169], v[132:133], 1, v[168:169]
	global_store_dword v[168:169], v159, off
	v_lshl_add_u64 v[168:169], v[168:169], 0, s[58:59]
	global_store_dword v[168:169], v170, off
	v_cvt_pk_bf16_f32 v167, v16, v17
	v_cvt_pk_bf16_f32 v169, v18, v19
	s_nop 0
	v_cndmask_b32_e64 v159, v167, v169, s[8:9]
	s_nop 1
	v_mov_b32_dpp v168, v159 quad_perm:[1,0,3,2] row_mask:0xf bank_mask:0xf bound_ctrl:1
	s_mov_b32 s12, 0x05040100
	s_mov_b32 s13, 0x07060302
	v_cndmask_b32_e32 v167, v167, v168, vcc
	v_cndmask_b32_e32 v169, v168, v169, vcc
	v_perm_b32 v159, v169, v167, s12
	v_perm_b32 v170, v169, v167, s13
	v_lshl_add_u64 v[164:165], v[164:165], 0, v[162:163]
	v_lshl_add_u64 v[164:165], v[132:133], 1, v[164:165]
	global_store_dword v[164:165], v159, off
	v_lshl_add_u64 v[164:165], v[164:165], 0, s[58:59]
	global_store_dword v[164:165], v170, off
	v_cvt_pk_bf16_f32 v164, v12, v13
	v_cvt_pk_bf16_f32 v167, v14, v15
	s_nop 0
	v_cndmask_b32_e64 v159, v164, v167, s[8:9]
	s_nop 1
	v_mov_b32_dpp v165, v159 quad_perm:[1,0,3,2] row_mask:0xf bank_mask:0xf bound_ctrl:1
	s_mov_b32 s12, 0x05040100
	s_mov_b32 s13, 0x07060302
	v_cndmask_b32_e32 v164, v164, v165, vcc
	v_cndmask_b32_e32 v167, v165, v167, vcc
	v_perm_b32 v159, v167, v164, s12
	v_perm_b32 v168, v167, v164, s13
	v_add_u32_e32 v164, 0xb0, v158
	v_and_b32_e32 v164, s34, v164
	v_lshlrev_b32_e32 v164, 1, v164
	v_mov_b32_e32 v165, v133
	v_lshl_add_u64 v[164:165], s[10:11], 0, v[164:165]
	v_lshl_add_u64 v[128:129], v[164:165], 0, v[128:129]
	v_lshl_add_u64 v[128:129], v[132:133], 1, v[128:129]
	global_store_dword v[128:129], v159, off
	v_lshl_add_u64 v[128:129], v[128:129], 0, s[58:59]
	global_store_dword v[128:129], v168, off
	v_cvt_pk_bf16_f32 v129, v8, v9
	v_cvt_pk_bf16_f32 v167, v10, v11
	s_nop 0
	v_cndmask_b32_e64 v128, v129, v167, s[8:9]
	s_nop 1
	v_mov_b32_dpp v159, v128 quad_perm:[1,0,3,2] row_mask:0xf bank_mask:0xf bound_ctrl:1
	s_mov_b32 s10, 0x05040100
	s_mov_b32 s11, 0x07060302
	v_cndmask_b32_e32 v129, v129, v159, vcc
	v_cndmask_b32_e32 v167, v159, v167, vcc
	v_perm_b32 v128, v167, v129, s10
	v_perm_b32 v168, v167, v129, s11
	v_lshl_add_u64 v[130:131], v[164:165], 0, v[130:131]
	v_lshl_add_u64 v[130:131], v[132:133], 1, v[130:131]
	global_store_dword v[130:131], v128, off
	v_lshl_add_u64 v[128:129], v[130:131], 0, s[58:59]
	global_store_dword v[128:129], v168, off
	v_cvt_pk_bf16_f32 v129, v4, v5
	v_cvt_pk_bf16_f32 v131, v6, v7
	s_nop 0
	v_cndmask_b32_e64 v128, v129, v131, s[8:9]
	s_nop 1
	v_mov_b32_dpp v130, v128 quad_perm:[1,0,3,2] row_mask:0xf bank_mask:0xf bound_ctrl:1
	s_mov_b32 s10, 0x05040100
	s_mov_b32 s11, 0x07060302
	v_cndmask_b32_e32 v129, v129, v130, vcc
	v_cndmask_b32_e32 v131, v130, v131, vcc
	v_perm_b32 v128, v131, v129, s10
	v_perm_b32 v159, v131, v129, s11
	v_lshl_add_u64 v[130:131], v[164:165], 0, v[160:161]
	v_lshl_add_u64 v[130:131], v[132:133], 1, v[130:131]
	global_store_dword v[130:131], v128, off
	v_lshl_add_u64 v[128:129], v[130:131], 0, s[58:59]
	global_store_dword v[128:129], v159, off
	v_cvt_pk_bf16_f32 v129, v0, v1
	v_cvt_pk_bf16_f32 v131, v2, v3
	s_nop 0
	v_cndmask_b32_e64 v128, v129, v131, s[8:9]
	s_nop 1
	v_mov_b32_dpp v130, v128 quad_perm:[1,0,3,2] row_mask:0xf bank_mask:0xf bound_ctrl:1
	s_mov_b32 s8, 0x05040100
	s_mov_b32 s9, 0x07060302
	v_cndmask_b32_e32 v129, v129, v130, vcc
	v_cndmask_b32_e32 v131, v130, v131, vcc
	v_perm_b32 v128, v131, v129, s8
	v_perm_b32 v159, v131, v129, s9
	v_lshl_add_u64 v[130:131], v[164:165], 0, v[162:163]
	v_lshl_add_u64 v[130:131], v[132:133], 1, v[130:131]
	global_store_dword v[130:131], v128, off
	v_lshl_add_u64 v[128:129], v[130:131], 0, s[58:59]
	global_store_dword v[128:129], v159, off
	s_mov_b64 s[8:9], 0

.LBB0_1103:
	s_ashr_i32 s9, s8, 31
	v_cmp_lt_i64_e32 vcc, s[10:11], v[144:145]
	s_lshl_b64 s[10:11], s[8:9], 19
	s_add_u32 s10, s15, s10
	s_addc_u32 s11, s26, s11
	s_and_b64 s[12:13], vcc, exec
	s_cselect_b32 s9, s11, s19
	s_cselect_b32 s42, s10, s18
	s_ashr_i32 s7, s6, 31
	s_lshl_b64 s[12:13], s[6:7], 19
	s_add_u32 s12, s27, s12
	s_addc_u32 s13, s28, s13
	s_and_b64 s[24:25], vcc, exec
	s_cselect_b32 s7, s13, s23
	s_cselect_b32 s43, s12, s22
	s_add_u32 s18, s18, 0x40080
	s_addc_u32 s19, s19, 0
	s_add_u32 s44, s22, 0x100
	v_mov_b32_e32 v0, 0
	s_addc_u32 s45, s23, 0
	s_mov_b32 s46, -2
	v_mov_b32_e32 v1, v0
	v_mov_b64_e32 v[2:3], 0
	v_mov_b64_e32 v[4:5], 0
	v_mov_b64_e32 v[6:7], 0
	v_mov_b64_e32 v[8:9], 0
	v_mov_b64_e32 v[10:11], 0
	v_mov_b64_e32 v[12:13], 0
	v_mov_b64_e32 v[14:15], 0
	v_mov_b64_e32 v[16:17], 0
	v_mov_b64_e32 v[18:19], 0
	v_mov_b64_e32 v[20:21], 0
	v_mov_b64_e32 v[22:23], 0
	v_mov_b64_e32 v[24:25], 0
	v_mov_b64_e32 v[26:27], 0
	v_mov_b64_e32 v[28:29], 0
	v_mov_b64_e32 v[30:31], 0
	v_mov_b64_e32 v[32:33], 0
	v_mov_b64_e32 v[34:35], 0
	v_mov_b64_e32 v[36:37], 0
	v_mov_b64_e32 v[38:39], 0
	v_mov_b64_e32 v[40:41], 0
	v_mov_b64_e32 v[42:43], 0
	v_mov_b64_e32 v[44:45], 0
	v_mov_b64_e32 v[46:47], 0
	v_mov_b64_e32 v[48:49], 0
	v_mov_b64_e32 v[50:51], 0
	v_mov_b64_e32 v[52:53], 0
	v_mov_b64_e32 v[54:55], 0
	v_mov_b64_e32 v[56:57], 0
	v_mov_b64_e32 v[58:59], 0
	v_mov_b64_e32 v[60:61], 0
	v_mov_b64_e32 v[62:63], 0
	v_mov_b64_e32 v[64:65], 0
	v_mov_b64_e32 v[66:67], 0
	v_mov_b64_e32 v[68:69], 0
	v_mov_b64_e32 v[70:71], 0
	v_mov_b64_e32 v[72:73], 0
	v_mov_b64_e32 v[74:75], 0
	v_mov_b64_e32 v[76:77], 0
	v_mov_b64_e32 v[78:79], 0
	v_mov_b64_e32 v[80:81], 0
	v_mov_b64_e32 v[82:83], 0
	v_mov_b64_e32 v[84:85], 0
	v_mov_b64_e32 v[86:87], 0
	v_mov_b64_e32 v[88:89], 0
	v_mov_b64_e32 v[90:91], 0
	v_mov_b64_e32 v[92:93], 0
	v_mov_b64_e32 v[94:95], 0
	v_mov_b64_e32 v[96:97], 0
	v_mov_b64_e32 v[98:99], 0
	v_mov_b64_e32 v[100:101], 0
	v_mov_b64_e32 v[102:103], 0
	v_mov_b64_e32 v[104:105], 0
	v_mov_b64_e32 v[106:107], 0
	v_mov_b64_e32 v[108:109], 0
	v_mov_b64_e32 v[110:111], 0
	v_mov_b64_e32 v[112:113], 0
	v_mov_b64_e32 v[114:115], 0
	v_mov_b64_e32 v[116:117], 0
	v_mov_b64_e32 v[118:119], 0
	v_mov_b64_e32 v[120:121], 0
	v_mov_b64_e32 v[122:123], 0
	v_mov_b64_e32 v[124:125], 0
	v_mov_b64_e32 v[126:127], 0
	v_add_u32_e32 v168, 0x10000, v154
	ds_read_b128 v[156:159], v168
	ds_read_b128 v[160:163], v168 offset:1024
	ds_read_b128 v[164:167], v168 offset:2048
	ds_read_b128 v[168:171], v168 offset:3072
.LBB0_1104:
	s_add_u32 s22, s18, 0xfffc0080
	s_addc_u32 s23, s19, -1
	s_add_i32 s47, 0, 0x10000
	s_cmp_eq_u32 s46, 12
	s_cselect_b32 s25, s9, s23
	s_cselect_b32 s24, s42, s22
	s_cselect_b32 s23, s7, s45
	s_cselect_b32 s22, s43, s44
	v_lshl_add_u64 v[152:153], s[18:19], 0, v[130:131]
	s_add_i32 m0, s17, 0xc000
	ds_read_b128 v[172:175], v155
	ds_read_b128 v[180:183], v155 offset:2048
	ds_read_b128 v[188:191], v155 offset:4096
	ds_read_b128 v[220:223], v155 offset:6144
	ds_read_b128 v[176:179], v155 offset:1024
	ds_read_b128 v[184:187], v155 offset:3072
	ds_read_b128 v[216:219], v155 offset:5120
	ds_read_b128 v[224:227], v155 offset:7168
	global_load_lds_dwordx4 v[152:153], off
	v_lshl_add_u64 v[152:153], s[18:19], 0, v[150:151]
	s_add_i32 m0, s17, 0xe000
	s_nop 0
	global_load_lds_dwordx4 v[152:153], off
	s_waitcnt lgkmcnt(8)
	s_waitcnt vmcnt(10)
	s_barrier
	s_waitcnt lgkmcnt(4)
	s_setprio 1
	v_mfma_f32_16x16x32_bf16 v[124:127], v[156:159], v[172:175], v[124:127]
	v_mfma_f32_16x16x32_bf16 v[120:123], v[164:167], v[172:175], v[120:123]
	v_mfma_f32_16x16x32_bf16 v[108:111], v[156:159], v[180:183], v[108:111]
	v_mfma_f32_16x16x32_bf16 v[104:107], v[164:167], v[180:183], v[104:107]
	v_mfma_f32_16x16x32_bf16 v[92:95], v[156:159], v[188:191], v[92:95]
	v_mfma_f32_16x16x32_bf16 v[88:91], v[164:167], v[188:191], v[88:91]
	v_mfma_f32_16x16x32_bf16 v[76:79], v[156:159], v[220:223], v[76:79]
	v_mfma_f32_16x16x32_bf16 v[72:75], v[164:167], v[220:223], v[72:75]
	s_waitcnt lgkmcnt(0)
	v_mfma_f32_16x16x32_bf16 v[124:127], v[160:163], v[176:179], v[124:127]
	v_mfma_f32_16x16x32_bf16 v[120:123], v[168:171], v[176:179], v[120:123]
	v_mfma_f32_16x16x32_bf16 v[108:111], v[160:163], v[184:187], v[108:111]
	v_mfma_f32_16x16x32_bf16 v[104:107], v[168:171], v[184:187], v[104:107]
	v_mfma_f32_16x16x32_bf16 v[92:95], v[160:163], v[216:219], v[92:95]
	v_mfma_f32_16x16x32_bf16 v[88:91], v[168:171], v[216:219], v[88:91]
	v_mfma_f32_16x16x32_bf16 v[76:79], v[160:163], v[224:227], v[76:79]
	v_mfma_f32_16x16x32_bf16 v[72:75], v[168:171], v[224:227], v[72:75]
	s_setprio 0
	s_barrier
	s_add_i32 s50, 0, 0x14000
	v_add_u32_e32 v152, s50, v154
	s_add_i32 s47, s47, s29
	ds_read_b128 v[228:231], v152
	ds_read_b128 v[236:239], v152 offset:2048
	ds_read_b128 v[232:235], v152 offset:1024
	ds_read_b128 v[240:243], v152 offset:3072
	v_lshl_add_u64 v[152:153], s[22:23], 0, v[132:133]
	s_mov_b32 m0, s47
	v_lshl_add_u64 v[244:245], s[22:23], 0, v[128:129]
	global_load_lds_dwordx4 v[152:153], off
	s_add_i32 m0, s47, 0x2000
	s_nop 0
	global_load_lds_dwordx4 v[244:245], off
	s_waitcnt vmcnt(10)
	s_barrier
	s_waitcnt lgkmcnt(2)
	s_setprio 1
	v_mfma_f32_16x16x32_bf16 v[116:119], v[228:231], v[172:175], v[116:119]
	v_mfma_f32_16x16x32_bf16 v[112:115], v[236:239], v[172:175], v[112:115]
	v_mfma_f32_16x16x32_bf16 v[100:103], v[228:231], v[180:183], v[100:103]
	v_mfma_f32_16x16x32_bf16 v[96:99], v[236:239], v[180:183], v[96:99]
	v_mfma_f32_16x16x32_bf16 v[84:87], v[228:231], v[188:191], v[84:87]
	v_mfma_f32_16x16x32_bf16 v[80:83], v[236:239], v[188:191], v[80:83]
	v_mfma_f32_16x16x32_bf16 v[68:71], v[228:231], v[220:223], v[68:71]
	v_mfma_f32_16x16x32_bf16 v[64:67], v[236:239], v[220:223], v[64:67]
	s_waitcnt lgkmcnt(0)
	v_mfma_f32_16x16x32_bf16 v[116:119], v[232:235], v[176:179], v[116:119]
	v_mfma_f32_16x16x32_bf16 v[112:115], v[240:243], v[176:179], v[112:115]
	v_mfma_f32_16x16x32_bf16 v[100:103], v[232:235], v[184:187], v[100:103]
	v_mfma_f32_16x16x32_bf16 v[96:99], v[240:243], v[184:187], v[96:99]
	v_mfma_f32_16x16x32_bf16 v[84:87], v[232:235], v[216:219], v[84:87]
	v_mfma_f32_16x16x32_bf16 v[80:83], v[240:243], v[216:219], v[80:83]
	v_mfma_f32_16x16x32_bf16 v[68:71], v[232:235], v[224:227], v[68:71]
	v_mfma_f32_16x16x32_bf16 v[64:67], v[240:243], v[224:227], v[64:67]
	s_setprio 0
	s_mov_b32 m0, s17
	v_lshl_add_u64 v[246:247], s[24:25], 0, v[132:133]
	s_barrier
	ds_read_b128 v[172:175], v155 offset:16384
	ds_read_b128 v[180:183], v155 offset:18432
	ds_read_b128 v[188:191], v155 offset:20480
	ds_read_b128 v[220:223], v155 offset:22528
	ds_read_b128 v[176:179], v155 offset:17408
	ds_read_b128 v[184:187], v155 offset:19456
	ds_read_b128 v[216:219], v155 offset:21504
	ds_read_b128 v[224:227], v155 offset:23552
	global_load_lds_dwordx4 v[246:247], off
	v_lshl_add_u64 v[248:249], s[24:25], 0, v[128:129]
	s_mov_b32 m0, s31
	s_nop 0
	global_load_lds_dwordx4 v[248:249], off
	s_waitcnt vmcnt(10)
	s_barrier
	s_waitcnt lgkmcnt(4)
	s_setprio 1
	v_mfma_f32_16x16x32_bf16 v[60:63], v[156:159], v[172:175], v[60:63]
	v_mfma_f32_16x16x32_bf16 v[56:59], v[164:167], v[172:175], v[56:59]
	v_mfma_f32_16x16x32_bf16 v[44:47], v[156:159], v[180:183], v[44:47]
	v_mfma_f32_16x16x32_bf16 v[40:43], v[164:167], v[180:183], v[40:43]
	v_mfma_f32_16x16x32_bf16 v[28:31], v[156:159], v[188:191], v[28:31]
	v_mfma_f32_16x16x32_bf16 v[24:27], v[164:167], v[188:191], v[24:27]
	v_mfma_f32_16x16x32_bf16 v[12:15], v[156:159], v[220:223], v[12:15]
	v_mfma_f32_16x16x32_bf16 v[8:11], v[164:167], v[220:223], v[8:11]
	s_waitcnt lgkmcnt(0)
	v_mfma_f32_16x16x32_bf16 v[60:63], v[160:163], v[176:179], v[60:63]
	v_mfma_f32_16x16x32_bf16 v[56:59], v[168:171], v[176:179], v[56:59]
	v_mfma_f32_16x16x32_bf16 v[44:47], v[160:163], v[184:187], v[44:47]
	v_mfma_f32_16x16x32_bf16 v[40:43], v[168:171], v[184:187], v[40:43]
	v_mfma_f32_16x16x32_bf16 v[28:31], v[160:163], v[216:219], v[28:31]
	v_mfma_f32_16x16x32_bf16 v[24:27], v[168:171], v[216:219], v[24:27]
	v_mfma_f32_16x16x32_bf16 v[12:15], v[160:163], v[224:227], v[12:15]
	v_mfma_f32_16x16x32_bf16 v[8:11], v[168:171], v[224:227], v[8:11]
	s_setprio 0
	s_barrier
	s_add_u32 s48, s22, 0x40000
	s_addc_u32 s49, s23, 0
	s_add_i32 s47, s50, s29
	v_lshl_add_u64 v[156:157], s[48:49], 0, v[132:133]
	s_mov_b32 m0, s47
	s_nop 0
	global_load_lds_dwordx4 v[156:157], off
	v_lshl_add_u64 v[156:157], s[48:49], 0, v[128:129]
	s_add_i32 m0, s47, 0x2000
	s_nop 0
	global_load_lds_dwordx4 v[156:157], off
	v_add_u32_e32 v168, 0x18000, v154
	ds_read_b128 v[156:159], v168
	ds_read_b128 v[160:163], v168 offset:1024
	ds_read_b128 v[164:167], v168 offset:2048
	ds_read_b128 v[168:171], v168 offset:3072
	s_waitcnt vmcnt(10)
	s_barrier
	s_setprio 1
	v_mfma_f32_16x16x32_bf16 v[52:55], v[228:231], v[172:175], v[52:55]
	v_mfma_f32_16x16x32_bf16 v[48:51], v[236:239], v[172:175], v[48:51]
	v_mfma_f32_16x16x32_bf16 v[36:39], v[228:231], v[180:183], v[36:39]
	v_mfma_f32_16x16x32_bf16 v[32:35], v[236:239], v[180:183], v[32:35]
	v_mfma_f32_16x16x32_bf16 v[20:23], v[228:231], v[188:191], v[20:23]
	v_mfma_f32_16x16x32_bf16 v[16:19], v[236:239], v[188:191], v[16:19]
	v_mfma_f32_16x16x32_bf16 v[4:7], v[228:231], v[220:223], v[4:7]
	v_mfma_f32_16x16x32_bf16 v[0:3], v[236:239], v[220:223], v[0:3]
	v_mfma_f32_16x16x32_bf16 v[52:55], v[232:235], v[176:179], v[52:55]
	v_mfma_f32_16x16x32_bf16 v[48:51], v[240:243], v[176:179], v[48:51]
	v_mfma_f32_16x16x32_bf16 v[36:39], v[232:235], v[184:187], v[36:39]
	v_mfma_f32_16x16x32_bf16 v[32:35], v[240:243], v[184:187], v[32:35]
	v_mfma_f32_16x16x32_bf16 v[20:23], v[232:235], v[216:219], v[20:23]
	v_mfma_f32_16x16x32_bf16 v[16:19], v[240:243], v[216:219], v[16:19]
	v_mfma_f32_16x16x32_bf16 v[4:7], v[232:235], v[224:227], v[4:7]
	v_mfma_f32_16x16x32_bf16 v[0:3], v[240:243], v[224:227], v[0:3]
	s_setprio 0
	s_add_i32 s47, 0, 0x18000
	s_barrier
	s_add_u32 s24, s24, 0x40000
	s_addc_u32 s25, s25, 0
	s_mov_b32 m0, s34
	v_lshl_add_u64 v[228:229], s[24:25], 0, v[132:133]
	ds_read_b128 v[172:175], v155 offset:32768
	ds_read_b128 v[180:183], v155 offset:34816
	ds_read_b128 v[188:191], v155 offset:36864
	ds_read_b128 v[220:223], v155 offset:38912
	ds_read_b128 v[176:179], v155 offset:33792
	ds_read_b128 v[184:187], v155 offset:35840
	ds_read_b128 v[216:219], v155 offset:37888
	ds_read_b128 v[224:227], v155 offset:39936
	global_load_lds_dwordx4 v[228:229], off
	v_lshl_add_u64 v[228:229], s[24:25], 0, v[128:129]
	s_mov_b32 m0, s35
	s_nop 0
	global_load_lds_dwordx4 v[228:229], off
	s_waitcnt lgkmcnt(8)
	s_waitcnt vmcnt(10)
	s_barrier
	s_waitcnt lgkmcnt(4)
	s_setprio 1
	v_mfma_f32_16x16x32_bf16 v[124:127], v[156:159], v[172:175], v[124:127]
	v_mfma_f32_16x16x32_bf16 v[120:123], v[164:167], v[172:175], v[120:123]
	v_mfma_f32_16x16x32_bf16 v[108:111], v[156:159], v[180:183], v[108:111]
	v_mfma_f32_16x16x32_bf16 v[104:107], v[164:167], v[180:183], v[104:107]
	v_mfma_f32_16x16x32_bf16 v[92:95], v[156:159], v[188:191], v[92:95]
	v_mfma_f32_16x16x32_bf16 v[88:91], v[164:167], v[188:191], v[88:91]
	v_mfma_f32_16x16x32_bf16 v[76:79], v[156:159], v[220:223], v[76:79]
	v_mfma_f32_16x16x32_bf16 v[72:75], v[164:167], v[220:223], v[72:75]
	s_waitcnt lgkmcnt(0)
	v_mfma_f32_16x16x32_bf16 v[124:127], v[160:163], v[176:179], v[124:127]
	v_mfma_f32_16x16x32_bf16 v[120:123], v[168:171], v[176:179], v[120:123]
	v_mfma_f32_16x16x32_bf16 v[108:111], v[160:163], v[184:187], v[108:111]
	v_mfma_f32_16x16x32_bf16 v[104:107], v[168:171], v[184:187], v[104:107]
	v_mfma_f32_16x16x32_bf16 v[92:95], v[160:163], v[216:219], v[92:95]
	v_mfma_f32_16x16x32_bf16 v[88:91], v[168:171], v[216:219], v[88:91]
	v_mfma_f32_16x16x32_bf16 v[76:79], v[160:163], v[224:227], v[76:79]
	v_mfma_f32_16x16x32_bf16 v[72:75], v[168:171], v[224:227], v[72:75]
	s_setprio 0
	s_barrier
	s_add_i32 s24, 0, 0x1c000
	s_add_i32 s25, s47, s29
	v_add_u32_e32 v200, s24, v154
	v_lshl_add_u64 v[152:153], v[152:153], 0, s[66:67]
	s_mov_b32 m0, s25
	ds_read_b128 v[228:231], v200
	ds_read_b128 v[236:239], v200 offset:2048
	ds_read_b128 v[232:235], v200 offset:1024
	ds_read_b128 v[240:243], v200 offset:3072
	global_load_lds_dwordx4 v[152:153], off
	v_lshl_add_u64 v[152:153], v[244:245], 0, s[66:67]
	s_add_i32 m0, s25, 0x2000
	s_nop 0
	global_load_lds_dwordx4 v[152:153], off
	s_waitcnt vmcnt(10)
	s_barrier
	s_waitcnt lgkmcnt(2)
	s_setprio 1
	v_mfma_f32_16x16x32_bf16 v[116:119], v[228:231], v[172:175], v[116:119]
	v_mfma_f32_16x16x32_bf16 v[112:115], v[236:239], v[172:175], v[112:115]
	v_mfma_f32_16x16x32_bf16 v[100:103], v[228:231], v[180:183], v[100:103]
	v_mfma_f32_16x16x32_bf16 v[96:99], v[236:239], v[180:183], v[96:99]
	v_mfma_f32_16x16x32_bf16 v[84:87], v[228:231], v[188:191], v[84:87]
	v_mfma_f32_16x16x32_bf16 v[80:83], v[236:239], v[188:191], v[80:83]
	v_mfma_f32_16x16x32_bf16 v[68:71], v[228:231], v[220:223], v[68:71]
	v_mfma_f32_16x16x32_bf16 v[64:67], v[236:239], v[220:223], v[64:67]
	s_waitcnt lgkmcnt(0)
	v_mfma_f32_16x16x32_bf16 v[116:119], v[232:235], v[176:179], v[116:119]
	v_mfma_f32_16x16x32_bf16 v[112:115], v[240:243], v[176:179], v[112:115]
	v_mfma_f32_16x16x32_bf16 v[100:103], v[232:235], v[184:187], v[100:103]
	v_mfma_f32_16x16x32_bf16 v[96:99], v[240:243], v[184:187], v[96:99]
	v_mfma_f32_16x16x32_bf16 v[84:87], v[232:235], v[216:219], v[84:87]
	v_mfma_f32_16x16x32_bf16 v[80:83], v[240:243], v[216:219], v[80:83]
	v_mfma_f32_16x16x32_bf16 v[68:71], v[232:235], v[224:227], v[68:71]
	v_mfma_f32_16x16x32_bf16 v[64:67], v[240:243], v[224:227], v[64:67]
	s_setprio 0
	s_mov_b32 m0, s36
	v_lshl_add_u64 v[152:153], v[246:247], 0, s[66:67]
	s_barrier
	ds_read_b128 v[172:175], v155 offset:49152
	ds_read_b128 v[180:183], v155 offset:51200
	ds_read_b128 v[188:191], v155 offset:53248
	ds_read_b128 v[220:223], v155 offset:55296
	ds_read_b128 v[176:179], v155 offset:50176
	ds_read_b128 v[184:187], v155 offset:52224
	ds_read_b128 v[216:219], v155 offset:54272
	ds_read_b128 v[224:227], v155 offset:56320
	global_load_lds_dwordx4 v[152:153], off
	v_lshl_add_u64 v[152:153], v[248:249], 0, s[66:67]
	s_mov_b32 m0, s37
	s_nop 0
	global_load_lds_dwordx4 v[152:153], off
	s_waitcnt vmcnt(10)
	s_barrier
	s_waitcnt lgkmcnt(4)
	s_setprio 1
	v_mfma_f32_16x16x32_bf16 v[60:63], v[156:159], v[172:175], v[60:63]
	v_mfma_f32_16x16x32_bf16 v[56:59], v[164:167], v[172:175], v[56:59]
	v_mfma_f32_16x16x32_bf16 v[44:47], v[156:159], v[180:183], v[44:47]
	v_mfma_f32_16x16x32_bf16 v[40:43], v[164:167], v[180:183], v[40:43]
	v_mfma_f32_16x16x32_bf16 v[28:31], v[156:159], v[188:191], v[28:31]
	v_mfma_f32_16x16x32_bf16 v[24:27], v[164:167], v[188:191], v[24:27]
	v_mfma_f32_16x16x32_bf16 v[12:15], v[156:159], v[220:223], v[12:15]
	v_mfma_f32_16x16x32_bf16 v[8:11], v[164:167], v[220:223], v[8:11]
	s_waitcnt lgkmcnt(0)
	v_mfma_f32_16x16x32_bf16 v[60:63], v[160:163], v[176:179], v[60:63]
	v_mfma_f32_16x16x32_bf16 v[56:59], v[168:171], v[176:179], v[56:59]
	v_mfma_f32_16x16x32_bf16 v[44:47], v[160:163], v[184:187], v[44:47]
	v_mfma_f32_16x16x32_bf16 v[40:43], v[168:171], v[184:187], v[40:43]
	v_mfma_f32_16x16x32_bf16 v[28:31], v[160:163], v[216:219], v[28:31]
	v_mfma_f32_16x16x32_bf16 v[24:27], v[168:171], v[216:219], v[24:27]
	v_mfma_f32_16x16x32_bf16 v[12:15], v[160:163], v[224:227], v[12:15]
	v_mfma_f32_16x16x32_bf16 v[8:11], v[168:171], v[224:227], v[8:11]
	s_setprio 0
	s_barrier
	s_add_u32 s22, s22, 0x40080
	s_addc_u32 s23, s23, 0
	s_add_i32 s24, s24, s29
	v_lshl_add_u64 v[152:153], s[22:23], 0, v[132:133]
	s_mov_b32 m0, s24
	s_nop 0
	global_load_lds_dwordx4 v[152:153], off
	v_lshl_add_u64 v[152:153], s[22:23], 0, v[128:129]
	s_add_i32 m0, s24, 0x2000
	s_nop 0
	global_load_lds_dwordx4 v[152:153], off
	v_add_u32_e32 v168, 0x10000, v154
	ds_read_b128 v[156:159], v168
	ds_read_b128 v[160:163], v168 offset:1024
	ds_read_b128 v[164:167], v168 offset:2048
	ds_read_b128 v[168:171], v168 offset:3072
	s_waitcnt vmcnt(10)
	s_barrier
	s_setprio 1
	v_mfma_f32_16x16x32_bf16 v[52:55], v[228:231], v[172:175], v[52:55]
	v_mfma_f32_16x16x32_bf16 v[48:51], v[236:239], v[172:175], v[48:51]
	v_mfma_f32_16x16x32_bf16 v[36:39], v[228:231], v[180:183], v[36:39]
	v_mfma_f32_16x16x32_bf16 v[32:35], v[236:239], v[180:183], v[32:35]
	v_mfma_f32_16x16x32_bf16 v[20:23], v[228:231], v[188:191], v[20:23]
	v_mfma_f32_16x16x32_bf16 v[16:19], v[236:239], v[188:191], v[16:19]
	v_mfma_f32_16x16x32_bf16 v[4:7], v[228:231], v[220:223], v[4:7]
	v_mfma_f32_16x16x32_bf16 v[0:3], v[236:239], v[220:223], v[0:3]
	v_mfma_f32_16x16x32_bf16 v[52:55], v[232:235], v[176:179], v[52:55]
	v_mfma_f32_16x16x32_bf16 v[48:51], v[240:243], v[176:179], v[48:51]
	v_mfma_f32_16x16x32_bf16 v[36:39], v[232:235], v[184:187], v[36:39]
	v_mfma_f32_16x16x32_bf16 v[32:35], v[240:243], v[184:187], v[32:35]
	v_mfma_f32_16x16x32_bf16 v[20:23], v[232:235], v[216:219], v[20:23]
	v_mfma_f32_16x16x32_bf16 v[16:19], v[240:243], v[216:219], v[16:19]
	v_mfma_f32_16x16x32_bf16 v[4:7], v[232:235], v[224:227], v[4:7]
	v_mfma_f32_16x16x32_bf16 v[0:3], v[240:243], v[224:227], v[0:3]
	s_setprio 0
	s_add_i32 s46, s46, 2
	s_add_u32 s18, s18, 0x100
	s_addc_u32 s19, s19, 0
	s_add_u32 s44, s44, 0x100
	s_addc_u32 s45, s45, 0
	s_cmp_gt_u32 s46, 13
	s_barrier
	s_cbranch_scc0 .LBB0_1104
	s_waitcnt lgkmcnt(0)
	v_mov_b32_e32 v153, v135
	s_mov_b64 s[18:19], s[0:1]
	s_load_dwordx2 s[18:19], s[18:19], 0x88
	s_nop 0
	v_readfirstlane_b32 s7, v153
	s_ashr_i32 s9, s7, 2
	s_lshr_b32 s7, s7, 1
	s_lshl_b32 s22, s41, 7
	s_and_b32 s7, s7, 0x60
	s_andn2_b32 s9, s9, 63
	s_or_b32 s7, s7, s22
	v_lshrrev_b32_e32 v152, 1, v153
	v_and_or_b32 v152, v152, 24, s7
	v_and_or_b32 v153, v153, 15, s9
	v_lshl_add_u32 v156, s16, 8, v153
	v_ashrrev_i32_e32 v153, 31, v152
	v_mov_b32_e32 v168, 0xbfb8aa3b
	v_mov_b32_e32 v169, 0xbfb8aa3b
	v_mov_b32_e32 v170, 1.0
	v_mov_b32_e32 v171, 1.0
	v_pk_mul_f32 v[160:161], v[124:125], v[168:169]
	v_pk_mul_f32 v[162:163], v[126:127], v[168:169]
	v_pk_mul_f32 v[164:165], v[116:117], v[168:169]
	v_pk_mul_f32 v[166:167], v[118:119], v[168:169]
	v_exp_f32_e32 v160, v160
	v_exp_f32_e32 v161, v161
	v_exp_f32_e32 v162, v162
	v_exp_f32_e32 v163, v163
	v_exp_f32_e32 v164, v164
	v_exp_f32_e32 v165, v165
	v_exp_f32_e32 v166, v166
	v_exp_f32_e32 v167, v167
	s_waitcnt lgkmcnt(0)
	v_lshl_add_u64 v[152:153], v[152:153], 1, s[18:19]
	s_mov_b64 s[18:19], 0xa2a4400
	v_lshl_add_u64 v[152:153], v[152:153], 0, s[18:19]
	s_and_b64 vcc, exec, s[4:5]
	s_mov_b32 s41, s6
	s_mov_b32 s16, s8
	s_mov_b64 s[22:23], s[12:13]
	v_pk_add_f32 v[160:161], v[160:161], v[170:171]
	v_pk_add_f32 v[162:163], v[162:163], v[170:171]
	v_pk_add_f32 v[164:165], v[164:165], v[170:171]
	v_pk_add_f32 v[166:167], v[166:167], v[170:171]
	v_rcp_f32_e32 v160, v160
	v_rcp_f32_e32 v161, v161
	v_rcp_f32_e32 v162, v162
	v_rcp_f32_e32 v163, v163
	v_rcp_f32_e32 v164, v164
	v_rcp_f32_e32 v165, v165
	v_rcp_f32_e32 v166, v166
	v_rcp_f32_e32 v167, v167
	v_mov_b32_e32 v158, v156
	v_mad_i64_i32 v[158:159], s[18:19], v158, s73, v[152:153]
	v_pk_mul_f32 v[124:125], v[124:125], v[160:161]
	v_pk_mul_f32 v[126:127], v[126:127], v[162:163]
	v_pk_mul_f32 v[116:117], v[116:117], v[164:165]
	v_pk_mul_f32 v[118:119], v[118:119], v[166:167]
	v_pk_mul_f32 v[120:121], v[120:121], v[124:125]
	v_pk_mul_f32 v[122:123], v[122:123], v[126:127]
	v_pk_mul_f32 v[112:113], v[112:113], v[116:117]
	v_pk_mul_f32 v[114:115], v[114:115], v[118:119]
	v_cvt_pk_bf16_f32 v120, v120, v121
	v_cvt_pk_bf16_f32 v121, v122, v123
	v_cvt_pk_bf16_f32 v122, v112, v113
	v_cvt_pk_bf16_f32 v123, v114, v115
	global_store_dwordx4 v[158:159], v[120:123], off sc1
	v_pk_mul_f32 v[160:161], v[108:109], v[168:169]
	v_pk_mul_f32 v[162:163], v[110:111], v[168:169]
	v_pk_mul_f32 v[164:165], v[100:101], v[168:169]
	v_pk_mul_f32 v[166:167], v[102:103], v[168:169]
	v_exp_f32_e32 v160, v160
	v_exp_f32_e32 v161, v161
	v_exp_f32_e32 v162, v162
	v_exp_f32_e32 v163, v163
	v_exp_f32_e32 v164, v164
	v_exp_f32_e32 v165, v165
	v_exp_f32_e32 v166, v166
	v_exp_f32_e32 v167, v167
	v_pk_add_f32 v[160:161], v[160:161], v[170:171]
	v_pk_add_f32 v[162:163], v[162:163], v[170:171]
	v_pk_add_f32 v[164:165], v[164:165], v[170:171]
	v_pk_add_f32 v[166:167], v[166:167], v[170:171]
	v_rcp_f32_e32 v160, v160
	v_rcp_f32_e32 v161, v161
	v_rcp_f32_e32 v162, v162
	v_rcp_f32_e32 v163, v163
	v_rcp_f32_e32 v164, v164
	v_rcp_f32_e32 v165, v165
	v_rcp_f32_e32 v166, v166
	v_rcp_f32_e32 v167, v167
	v_add_u32_e32 v158, 0x10, v156
	v_mad_i64_i32 v[158:159], s[18:19], v158, s73, v[152:153]
	v_pk_mul_f32 v[108:109], v[108:109], v[160:161]
	v_pk_mul_f32 v[110:111], v[110:111], v[162:163]
	v_pk_mul_f32 v[100:101], v[100:101], v[164:165]
	v_pk_mul_f32 v[102:103], v[102:103], v[166:167]
	v_pk_mul_f32 v[104:105], v[104:105], v[108:109]
	v_pk_mul_f32 v[106:107], v[106:107], v[110:111]
	v_pk_mul_f32 v[96:97], v[96:97], v[100:101]
	v_pk_mul_f32 v[98:99], v[98:99], v[102:103]
	v_cvt_pk_bf16_f32 v104, v104, v105
	v_cvt_pk_bf16_f32 v105, v106, v107
	v_cvt_pk_bf16_f32 v106, v96, v97
	v_cvt_pk_bf16_f32 v107, v98, v99
	global_store_dwordx4 v[158:159], v[104:107], off sc1
	v_pk_mul_f32 v[160:161], v[92:93], v[168:169]
	v_pk_mul_f32 v[162:163], v[94:95], v[168:169]
	v_pk_mul_f32 v[164:165], v[84:85], v[168:169]
	v_pk_mul_f32 v[166:167], v[86:87], v[168:169]
	v_exp_f32_e32 v160, v160
	v_exp_f32_e32 v161, v161
	v_exp_f32_e32 v162, v162
	v_exp_f32_e32 v163, v163
	v_exp_f32_e32 v164, v164
	v_exp_f32_e32 v165, v165
	v_exp_f32_e32 v166, v166
	v_exp_f32_e32 v167, v167
	v_pk_add_f32 v[160:161], v[160:161], v[170:171]
	v_pk_add_f32 v[162:163], v[162:163], v[170:171]
	v_pk_add_f32 v[164:165], v[164:165], v[170:171]
	v_pk_add_f32 v[166:167], v[166:167], v[170:171]
	v_rcp_f32_e32 v160, v160
	v_rcp_f32_e32 v161, v161
	v_rcp_f32_e32 v162, v162
	v_rcp_f32_e32 v163, v163
	v_rcp_f32_e32 v164, v164
	v_rcp_f32_e32 v165, v165
	v_rcp_f32_e32 v166, v166
	v_rcp_f32_e32 v167, v167
	v_add_u32_e32 v158, 0x20, v156
	v_mad_i64_i32 v[158:159], s[18:19], v158, s73, v[152:153]
	v_pk_mul_f32 v[92:93], v[92:93], v[160:161]
	v_pk_mul_f32 v[94:95], v[94:95], v[162:163]
	v_pk_mul_f32 v[84:85], v[84:85], v[164:165]
	v_pk_mul_f32 v[86:87], v[86:87], v[166:167]
	v_pk_mul_f32 v[88:89], v[88:89], v[92:93]
	v_pk_mul_f32 v[90:91], v[90:91], v[94:95]
	v_pk_mul_f32 v[80:81], v[80:81], v[84:85]
	v_pk_mul_f32 v[82:83], v[82:83], v[86:87]
	v_cvt_pk_bf16_f32 v88, v88, v89
	v_cvt_pk_bf16_f32 v89, v90, v91
	v_cvt_pk_bf16_f32 v90, v80, v81
	v_cvt_pk_bf16_f32 v91, v82, v83
	global_store_dwordx4 v[158:159], v[88:91], off sc1
	v_pk_mul_f32 v[160:161], v[76:77], v[168:169]
	v_pk_mul_f32 v[162:163], v[78:79], v[168:169]
	v_pk_mul_f32 v[164:165], v[68:69], v[168:169]
	v_pk_mul_f32 v[166:167], v[70:71], v[168:169]
	v_exp_f32_e32 v160, v160
	v_exp_f32_e32 v161, v161
	v_exp_f32_e32 v162, v162
	v_exp_f32_e32 v163, v163
	v_exp_f32_e32 v164, v164
	v_exp_f32_e32 v165, v165
	v_exp_f32_e32 v166, v166
	v_exp_f32_e32 v167, v167
	v_pk_add_f32 v[160:161], v[160:161], v[170:171]
	v_pk_add_f32 v[162:163], v[162:163], v[170:171]
	v_pk_add_f32 v[164:165], v[164:165], v[170:171]
	v_pk_add_f32 v[166:167], v[166:167], v[170:171]
	v_rcp_f32_e32 v160, v160
	v_rcp_f32_e32 v161, v161
	v_rcp_f32_e32 v162, v162
	v_rcp_f32_e32 v163, v163
	v_rcp_f32_e32 v164, v164
	v_rcp_f32_e32 v165, v165
	v_rcp_f32_e32 v166, v166
	v_rcp_f32_e32 v167, v167
	v_add_u32_e32 v158, 0x30, v156
	v_mad_i64_i32 v[158:159], s[18:19], v158, s73, v[152:153]
	v_pk_mul_f32 v[76:77], v[76:77], v[160:161]
	v_pk_mul_f32 v[78:79], v[78:79], v[162:163]
	v_pk_mul_f32 v[68:69], v[68:69], v[164:165]
	v_pk_mul_f32 v[70:71], v[70:71], v[166:167]
	v_pk_mul_f32 v[72:73], v[72:73], v[76:77]
	v_pk_mul_f32 v[74:75], v[74:75], v[78:79]
	v_pk_mul_f32 v[64:65], v[64:65], v[68:69]
	v_pk_mul_f32 v[66:67], v[66:67], v[70:71]
	v_cvt_pk_bf16_f32 v72, v72, v73
	v_cvt_pk_bf16_f32 v73, v74, v75
	v_cvt_pk_bf16_f32 v74, v64, v65
	v_cvt_pk_bf16_f32 v75, v66, v67
	global_store_dwordx4 v[158:159], v[72:75], off sc1
	v_pk_mul_f32 v[160:161], v[60:61], v[168:169]
	v_pk_mul_f32 v[162:163], v[62:63], v[168:169]
	v_pk_mul_f32 v[164:165], v[52:53], v[168:169]
	v_pk_mul_f32 v[166:167], v[54:55], v[168:169]
	v_exp_f32_e32 v160, v160
	v_exp_f32_e32 v161, v161
	v_exp_f32_e32 v162, v162
	v_exp_f32_e32 v163, v163
	v_exp_f32_e32 v164, v164
	v_exp_f32_e32 v165, v165
	v_exp_f32_e32 v166, v166
	v_exp_f32_e32 v167, v167
	v_pk_add_f32 v[160:161], v[160:161], v[170:171]
	v_pk_add_f32 v[162:163], v[162:163], v[170:171]
	v_pk_add_f32 v[164:165], v[164:165], v[170:171]
	v_pk_add_f32 v[166:167], v[166:167], v[170:171]
	v_rcp_f32_e32 v160, v160
	v_rcp_f32_e32 v161, v161
	v_rcp_f32_e32 v162, v162
	v_rcp_f32_e32 v163, v163
	v_rcp_f32_e32 v164, v164
	v_rcp_f32_e32 v165, v165
	v_rcp_f32_e32 v166, v166
	v_rcp_f32_e32 v167, v167
	v_add_u32_e32 v158, 0x80, v156
	v_mad_i64_i32 v[158:159], s[18:19], v158, s73, v[152:153]
	v_pk_mul_f32 v[60:61], v[60:61], v[160:161]
	v_pk_mul_f32 v[62:63], v[62:63], v[162:163]
	v_pk_mul_f32 v[52:53], v[52:53], v[164:165]
	v_pk_mul_f32 v[54:55], v[54:55], v[166:167]
	v_pk_mul_f32 v[56:57], v[56:57], v[60:61]
	v_pk_mul_f32 v[58:59], v[58:59], v[62:63]
	v_pk_mul_f32 v[48:49], v[48:49], v[52:53]
	v_pk_mul_f32 v[50:51], v[50:51], v[54:55]
	v_cvt_pk_bf16_f32 v56, v56, v57
	v_cvt_pk_bf16_f32 v57, v58, v59
	v_cvt_pk_bf16_f32 v58, v48, v49
	v_cvt_pk_bf16_f32 v59, v50, v51
	global_store_dwordx4 v[158:159], v[56:59], off sc1
	v_pk_mul_f32 v[160:161], v[44:45], v[168:169]
	v_pk_mul_f32 v[162:163], v[46:47], v[168:169]
	v_pk_mul_f32 v[164:165], v[36:37], v[168:169]
	v_pk_mul_f32 v[166:167], v[38:39], v[168:169]
	v_exp_f32_e32 v160, v160
	v_exp_f32_e32 v161, v161
	v_exp_f32_e32 v162, v162
	v_exp_f32_e32 v163, v163
	v_exp_f32_e32 v164, v164
	v_exp_f32_e32 v165, v165
	v_exp_f32_e32 v166, v166
	v_exp_f32_e32 v167, v167
	v_pk_add_f32 v[160:161], v[160:161], v[170:171]
	v_pk_add_f32 v[162:163], v[162:163], v[170:171]
	v_pk_add_f32 v[164:165], v[164:165], v[170:171]
	v_pk_add_f32 v[166:167], v[166:167], v[170:171]
	v_rcp_f32_e32 v160, v160
	v_rcp_f32_e32 v161, v161
	v_rcp_f32_e32 v162, v162
	v_rcp_f32_e32 v163, v163
	v_rcp_f32_e32 v164, v164
	v_rcp_f32_e32 v165, v165
	v_rcp_f32_e32 v166, v166
	v_rcp_f32_e32 v167, v167
	v_add_u32_e32 v158, 0x90, v156
	v_mad_i64_i32 v[158:159], s[18:19], v158, s73, v[152:153]
	v_pk_mul_f32 v[44:45], v[44:45], v[160:161]
	v_pk_mul_f32 v[46:47], v[46:47], v[162:163]
	v_pk_mul_f32 v[36:37], v[36:37], v[164:165]
	v_pk_mul_f32 v[38:39], v[38:39], v[166:167]
	v_pk_mul_f32 v[40:41], v[40:41], v[44:45]
	v_pk_mul_f32 v[42:43], v[42:43], v[46:47]
	v_pk_mul_f32 v[32:33], v[32:33], v[36:37]
	v_pk_mul_f32 v[34:35], v[34:35], v[38:39]
	v_cvt_pk_bf16_f32 v40, v40, v41
	v_cvt_pk_bf16_f32 v41, v42, v43
	v_cvt_pk_bf16_f32 v42, v32, v33
	v_cvt_pk_bf16_f32 v43, v34, v35
	global_store_dwordx4 v[158:159], v[40:43], off sc1
	v_pk_mul_f32 v[160:161], v[28:29], v[168:169]
	v_pk_mul_f32 v[162:163], v[30:31], v[168:169]
	v_pk_mul_f32 v[164:165], v[20:21], v[168:169]
	v_pk_mul_f32 v[166:167], v[22:23], v[168:169]
	v_exp_f32_e32 v160, v160
	v_exp_f32_e32 v161, v161
	v_exp_f32_e32 v162, v162
	v_exp_f32_e32 v163, v163
	v_exp_f32_e32 v164, v164
	v_exp_f32_e32 v165, v165
	v_exp_f32_e32 v166, v166
	v_exp_f32_e32 v167, v167
	v_pk_add_f32 v[160:161], v[160:161], v[170:171]
	v_pk_add_f32 v[162:163], v[162:163], v[170:171]
	v_pk_add_f32 v[164:165], v[164:165], v[170:171]
	v_pk_add_f32 v[166:167], v[166:167], v[170:171]
	v_rcp_f32_e32 v160, v160
	v_rcp_f32_e32 v161, v161
	v_rcp_f32_e32 v162, v162
	v_rcp_f32_e32 v163, v163
	v_rcp_f32_e32 v164, v164
	v_rcp_f32_e32 v165, v165
	v_rcp_f32_e32 v166, v166
	v_rcp_f32_e32 v167, v167
	v_add_u32_e32 v158, 0xa0, v156
	v_mad_i64_i32 v[158:159], s[18:19], v158, s73, v[152:153]
	v_pk_mul_f32 v[28:29], v[28:29], v[160:161]
	v_pk_mul_f32 v[30:31], v[30:31], v[162:163]
	v_pk_mul_f32 v[20:21], v[20:21], v[164:165]
	v_pk_mul_f32 v[22:23], v[22:23], v[166:167]
	v_pk_mul_f32 v[24:25], v[24:25], v[28:29]
	v_pk_mul_f32 v[26:27], v[26:27], v[30:31]
	v_pk_mul_f32 v[16:17], v[16:17], v[20:21]
	v_pk_mul_f32 v[18:19], v[18:19], v[22:23]
	v_cvt_pk_bf16_f32 v24, v24, v25
	v_cvt_pk_bf16_f32 v25, v26, v27
	v_cvt_pk_bf16_f32 v26, v16, v17
	v_cvt_pk_bf16_f32 v27, v18, v19
	global_store_dwordx4 v[158:159], v[24:27], off sc1
	v_pk_mul_f32 v[160:161], v[12:13], v[168:169]
	v_pk_mul_f32 v[162:163], v[14:15], v[168:169]
	v_pk_mul_f32 v[164:165], v[4:5], v[168:169]
	v_pk_mul_f32 v[166:167], v[6:7], v[168:169]
	v_exp_f32_e32 v160, v160
	v_exp_f32_e32 v161, v161
	v_exp_f32_e32 v162, v162
	v_exp_f32_e32 v163, v163
	v_exp_f32_e32 v164, v164
	v_exp_f32_e32 v165, v165
	v_exp_f32_e32 v166, v166
	v_exp_f32_e32 v167, v167
	v_pk_add_f32 v[160:161], v[160:161], v[170:171]
	v_pk_add_f32 v[162:163], v[162:163], v[170:171]
	v_pk_add_f32 v[164:165], v[164:165], v[170:171]
	v_pk_add_f32 v[166:167], v[166:167], v[170:171]
	v_rcp_f32_e32 v160, v160
	v_rcp_f32_e32 v161, v161
	v_rcp_f32_e32 v162, v162
	v_rcp_f32_e32 v163, v163
	v_rcp_f32_e32 v164, v164
	v_rcp_f32_e32 v165, v165
	v_rcp_f32_e32 v166, v166
	v_rcp_f32_e32 v167, v167
	v_add_u32_e32 v158, 0xb0, v156
	v_mad_i64_i32 v[158:159], s[18:19], v158, s73, v[152:153]
	v_pk_mul_f32 v[12:13], v[12:13], v[160:161]
	v_pk_mul_f32 v[14:15], v[14:15], v[162:163]
	v_pk_mul_f32 v[4:5], v[4:5], v[164:165]
	v_pk_mul_f32 v[6:7], v[6:7], v[166:167]
	v_pk_mul_f32 v[8:9], v[8:9], v[12:13]
	v_pk_mul_f32 v[10:11], v[10:11], v[14:15]
	v_pk_mul_f32 v[0:1], v[0:1], v[4:5]
	v_pk_mul_f32 v[2:3], v[2:3], v[6:7]
	v_cvt_pk_bf16_f32 v8, v8, v9
	v_cvt_pk_bf16_f32 v9, v10, v11
	v_cvt_pk_bf16_f32 v10, v0, v1
	v_cvt_pk_bf16_f32 v11, v2, v3
	global_store_dwordx4 v[158:159], v[8:11], off sc1
	s_mov_b64 s[18:19], s[10:11]
	s_cbranch_vccz .LBB0_1101
	s_waitcnt vmcnt(0)
	s_cmpk_gt_u32 s14, 0xff
	s_cbranch_scc1 .LBB0_1108
	s_barrier

.LBB0_1233:
	s_add_u32 s8, s12, 0x80
	s_addc_u32 s9, s13, 0
	s_add_u32 s38, s10, 0x100
	v_mov_b32_e32 v0, 0
	s_addc_u32 s39, s11, 0
	s_mov_b32 s10, 0
	v_mov_b32_e32 v1, v0
	v_mov_b64_e32 v[2:3], 0
	v_mov_b64_e32 v[4:5], 0
	v_mov_b64_e32 v[6:7], 0
	v_mov_b64_e32 v[8:9], 0
	v_mov_b64_e32 v[10:11], 0
	v_mov_b64_e32 v[12:13], 0
	v_mov_b64_e32 v[14:15], 0
	v_mov_b64_e32 v[16:17], 0
	v_mov_b64_e32 v[18:19], 0
	v_mov_b64_e32 v[20:21], 0
	v_mov_b64_e32 v[22:23], 0
	v_mov_b64_e32 v[24:25], 0
	v_mov_b64_e32 v[26:27], 0
	v_mov_b64_e32 v[28:29], 0
	v_mov_b64_e32 v[30:31], 0
	v_mov_b64_e32 v[32:33], 0
	v_mov_b64_e32 v[34:35], 0
	v_mov_b64_e32 v[36:37], 0
	v_mov_b64_e32 v[38:39], 0
	v_mov_b64_e32 v[40:41], 0
	v_mov_b64_e32 v[42:43], 0
	v_mov_b64_e32 v[44:45], 0
	v_mov_b64_e32 v[46:47], 0
	v_mov_b64_e32 v[48:49], 0
	v_mov_b64_e32 v[50:51], 0
	v_mov_b64_e32 v[52:53], 0
	v_mov_b64_e32 v[54:55], 0
	v_mov_b64_e32 v[56:57], 0
	v_mov_b64_e32 v[58:59], 0
	v_mov_b64_e32 v[60:61], 0
	v_mov_b64_e32 v[62:63], 0
	v_mov_b64_e32 v[64:65], 0
	v_mov_b64_e32 v[66:67], 0
	v_mov_b64_e32 v[68:69], 0
	v_mov_b64_e32 v[70:71], 0
	v_mov_b64_e32 v[72:73], 0
	v_mov_b64_e32 v[74:75], 0
	v_mov_b64_e32 v[76:77], 0
	v_mov_b64_e32 v[78:79], 0
	v_mov_b64_e32 v[80:81], 0
	v_mov_b64_e32 v[82:83], 0
	v_mov_b64_e32 v[84:85], 0
	v_mov_b64_e32 v[86:87], 0
	v_mov_b64_e32 v[88:89], 0
	v_mov_b64_e32 v[90:91], 0
	v_mov_b64_e32 v[92:93], 0
	v_mov_b64_e32 v[94:95], 0
	v_mov_b64_e32 v[96:97], 0
	v_mov_b64_e32 v[98:99], 0
	v_mov_b64_e32 v[100:101], 0
	v_mov_b64_e32 v[102:103], 0
	v_mov_b64_e32 v[104:105], 0
	v_mov_b64_e32 v[106:107], 0
	v_mov_b64_e32 v[108:109], 0
	v_mov_b64_e32 v[110:111], 0
	v_mov_b64_e32 v[112:113], 0
	v_mov_b64_e32 v[114:115], 0
	v_mov_b64_e32 v[116:117], 0
	v_mov_b64_e32 v[118:119], 0
	v_mov_b64_e32 v[120:121], 0
	v_mov_b64_e32 v[122:123], 0
	v_mov_b64_e32 v[124:125], 0
	v_mov_b64_e32 v[126:127], 0
	v_add_u32_e32 v168, 0x10000, v154
	ds_read_b128 v[156:159], v168
	ds_read_b128 v[160:163], v168 offset:1024
	ds_read_b128 v[164:167], v168 offset:2048
	ds_read_b128 v[168:171], v168 offset:3072
.LBB0_1234:
	s_add_i32 s40, s10, 2
	s_add_u32 s12, s8, 0x80
	s_addc_u32 s11, s9, 0
	s_add_i32 s41, 0, 0x10000
	s_cmp_eq_u32 s29, s10
	s_cselect_b32 s10, s2, s12
	s_cselect_b32 s11, s3, s11
	s_cselect_b32 s13, s7, s39
	s_cselect_b32 s12, s6, s38
	v_lshl_add_u64 v[152:153], s[8:9], 0, v[130:131]
	s_add_i32 m0, s22, 0xc000
	ds_read_b128 v[172:175], v155
	ds_read_b128 v[180:183], v155 offset:2048
	ds_read_b128 v[188:191], v155 offset:4096
	ds_read_b128 v[220:223], v155 offset:6144
	ds_read_b128 v[176:179], v155 offset:1024
	ds_read_b128 v[184:187], v155 offset:3072
	ds_read_b128 v[216:219], v155 offset:5120
	ds_read_b128 v[224:227], v155 offset:7168
	global_load_lds_dwordx4 v[152:153], off
	v_lshl_add_u64 v[152:153], s[8:9], 0, v[150:151]
	s_add_i32 m0, s22, 0xe000
	s_nop 0
	global_load_lds_dwordx4 v[152:153], off
	s_waitcnt lgkmcnt(8)
	s_waitcnt vmcnt(10)
	s_barrier
	s_waitcnt lgkmcnt(4)
	s_setprio 1
	v_mfma_f32_16x16x32_bf16 v[124:127], v[156:159], v[172:175], v[124:127]
	v_mfma_f32_16x16x32_bf16 v[120:123], v[164:167], v[172:175], v[120:123]
	v_mfma_f32_16x16x32_bf16 v[116:119], v[156:159], v[180:183], v[116:119]
	v_mfma_f32_16x16x32_bf16 v[108:111], v[164:167], v[180:183], v[108:111]
	v_mfma_f32_16x16x32_bf16 v[100:103], v[156:159], v[188:191], v[100:103]
	v_mfma_f32_16x16x32_bf16 v[92:95], v[164:167], v[188:191], v[92:95]
	v_mfma_f32_16x16x32_bf16 v[84:87], v[156:159], v[220:223], v[84:87]
	v_mfma_f32_16x16x32_bf16 v[76:79], v[164:167], v[220:223], v[76:79]
	s_waitcnt lgkmcnt(0)
	v_mfma_f32_16x16x32_bf16 v[124:127], v[160:163], v[176:179], v[124:127]
	v_mfma_f32_16x16x32_bf16 v[120:123], v[168:171], v[176:179], v[120:123]
	v_mfma_f32_16x16x32_bf16 v[116:119], v[160:163], v[184:187], v[116:119]
	v_mfma_f32_16x16x32_bf16 v[108:111], v[168:171], v[184:187], v[108:111]
	v_mfma_f32_16x16x32_bf16 v[100:103], v[160:163], v[216:219], v[100:103]
	v_mfma_f32_16x16x32_bf16 v[92:95], v[168:171], v[216:219], v[92:95]
	v_mfma_f32_16x16x32_bf16 v[84:87], v[160:163], v[224:227], v[84:87]
	v_mfma_f32_16x16x32_bf16 v[76:79], v[168:171], v[224:227], v[76:79]
	s_setprio 0
	s_barrier
	s_add_i32 s42, 0, 0x14000
	v_add_u32_e32 v152, s42, v154
	s_add_i32 s41, s41, s19
	ds_read_b128 v[228:231], v152
	ds_read_b128 v[236:239], v152 offset:2048
	ds_read_b128 v[232:235], v152 offset:1024
	ds_read_b128 v[240:243], v152 offset:3072
	v_lshl_add_u64 v[152:153], s[12:13], 0, v[132:133]
	s_mov_b32 m0, s41
	v_lshl_add_u64 v[244:245], s[12:13], 0, v[128:129]
	global_load_lds_dwordx4 v[152:153], off
	s_add_i32 m0, s41, 0x2000
	s_nop 0
	global_load_lds_dwordx4 v[244:245], off
	s_waitcnt vmcnt(10)
	s_barrier
	s_waitcnt lgkmcnt(2)
	s_setprio 1
	v_mfma_f32_16x16x32_bf16 v[112:115], v[228:231], v[172:175], v[112:115]
	v_mfma_f32_16x16x32_bf16 v[104:107], v[236:239], v[172:175], v[104:107]
	v_mfma_f32_16x16x32_bf16 v[96:99], v[228:231], v[180:183], v[96:99]
	v_mfma_f32_16x16x32_bf16 v[88:91], v[236:239], v[180:183], v[88:91]
	v_mfma_f32_16x16x32_bf16 v[80:83], v[228:231], v[188:191], v[80:83]
	v_mfma_f32_16x16x32_bf16 v[72:75], v[236:239], v[188:191], v[72:75]
	v_mfma_f32_16x16x32_bf16 v[68:71], v[228:231], v[220:223], v[68:71]
	v_mfma_f32_16x16x32_bf16 v[64:67], v[236:239], v[220:223], v[64:67]
	s_waitcnt lgkmcnt(0)
	v_mfma_f32_16x16x32_bf16 v[112:115], v[232:235], v[176:179], v[112:115]
	v_mfma_f32_16x16x32_bf16 v[104:107], v[240:243], v[176:179], v[104:107]
	v_mfma_f32_16x16x32_bf16 v[96:99], v[232:235], v[184:187], v[96:99]
	v_mfma_f32_16x16x32_bf16 v[88:91], v[240:243], v[184:187], v[88:91]
	v_mfma_f32_16x16x32_bf16 v[80:83], v[232:235], v[216:219], v[80:83]
	v_mfma_f32_16x16x32_bf16 v[72:75], v[240:243], v[216:219], v[72:75]
	v_mfma_f32_16x16x32_bf16 v[68:71], v[232:235], v[224:227], v[68:71]
	v_mfma_f32_16x16x32_bf16 v[64:67], v[240:243], v[224:227], v[64:67]
	s_setprio 0
	s_mov_b32 m0, s22
	v_lshl_add_u64 v[246:247], s[10:11], 0, v[132:133]
	s_barrier
	ds_read_b128 v[172:175], v155 offset:16384
	ds_read_b128 v[180:183], v155 offset:18432
	ds_read_b128 v[188:191], v155 offset:20480
	ds_read_b128 v[220:223], v155 offset:22528
	ds_read_b128 v[176:179], v155 offset:17408
	ds_read_b128 v[184:187], v155 offset:19456
	ds_read_b128 v[216:219], v155 offset:21504
	ds_read_b128 v[224:227], v155 offset:23552
	global_load_lds_dwordx4 v[246:247], off
	v_lshl_add_u64 v[248:249], s[10:11], 0, v[128:129]
	s_mov_b32 m0, s23
	s_nop 0
	global_load_lds_dwordx4 v[248:249], off
	s_waitcnt vmcnt(10)
	s_barrier
	s_waitcnt lgkmcnt(4)
	s_setprio 1
	v_mfma_f32_16x16x32_bf16 v[60:63], v[156:159], v[172:175], v[60:63]
	v_mfma_f32_16x16x32_bf16 v[56:59], v[164:167], v[172:175], v[56:59]
	v_mfma_f32_16x16x32_bf16 v[52:55], v[156:159], v[180:183], v[52:55]
	v_mfma_f32_16x16x32_bf16 v[44:47], v[164:167], v[180:183], v[44:47]
	v_mfma_f32_16x16x32_bf16 v[36:39], v[156:159], v[188:191], v[36:39]
	v_mfma_f32_16x16x32_bf16 v[28:31], v[164:167], v[188:191], v[28:31]
	v_mfma_f32_16x16x32_bf16 v[20:23], v[156:159], v[220:223], v[20:23]
	v_mfma_f32_16x16x32_bf16 v[12:15], v[164:167], v[220:223], v[12:15]
	s_waitcnt lgkmcnt(0)
	v_mfma_f32_16x16x32_bf16 v[60:63], v[160:163], v[176:179], v[60:63]
	v_mfma_f32_16x16x32_bf16 v[56:59], v[168:171], v[176:179], v[56:59]
	v_mfma_f32_16x16x32_bf16 v[52:55], v[160:163], v[184:187], v[52:55]
	v_mfma_f32_16x16x32_bf16 v[44:47], v[168:171], v[184:187], v[44:47]
	v_mfma_f32_16x16x32_bf16 v[36:39], v[160:163], v[216:219], v[36:39]
	v_mfma_f32_16x16x32_bf16 v[28:31], v[168:171], v[216:219], v[28:31]
	v_mfma_f32_16x16x32_bf16 v[20:23], v[160:163], v[224:227], v[20:23]
	v_mfma_f32_16x16x32_bf16 v[12:15], v[168:171], v[224:227], v[12:15]
	s_setprio 0
	s_barrier
	s_add_u32 s12, s12, s58
	s_addc_u32 s13, s13, 0
	s_add_i32 s41, s42, s19
	v_lshl_add_u64 v[250:251], s[12:13], 0, v[132:133]
	s_mov_b32 m0, s41
	v_lshl_add_u64 v[252:253], s[12:13], 0, v[128:129]
	global_load_lds_dwordx4 v[250:251], off
	s_add_i32 m0, s41, 0x2000
	s_nop 0
	global_load_lds_dwordx4 v[252:253], off
	v_add_u32_e32 v168, 0x18000, v154
	ds_read_b128 v[156:159], v168
	ds_read_b128 v[160:163], v168 offset:1024
	ds_read_b128 v[164:167], v168 offset:2048
	ds_read_b128 v[168:171], v168 offset:3072
	s_waitcnt vmcnt(10)
	s_barrier
	s_setprio 1
	v_mfma_f32_16x16x32_bf16 v[48:51], v[228:231], v[172:175], v[48:51]
	v_mfma_f32_16x16x32_bf16 v[40:43], v[236:239], v[172:175], v[40:43]
	v_mfma_f32_16x16x32_bf16 v[32:35], v[228:231], v[180:183], v[32:35]
	v_mfma_f32_16x16x32_bf16 v[24:27], v[236:239], v[180:183], v[24:27]
	v_mfma_f32_16x16x32_bf16 v[16:19], v[228:231], v[188:191], v[16:19]
	v_mfma_f32_16x16x32_bf16 v[8:11], v[236:239], v[188:191], v[8:11]
	v_mfma_f32_16x16x32_bf16 v[4:7], v[228:231], v[220:223], v[4:7]
	v_mfma_f32_16x16x32_bf16 v[0:3], v[236:239], v[220:223], v[0:3]
	v_mfma_f32_16x16x32_bf16 v[48:51], v[232:235], v[176:179], v[48:51]
	v_mfma_f32_16x16x32_bf16 v[40:43], v[240:243], v[176:179], v[40:43]
	v_mfma_f32_16x16x32_bf16 v[32:35], v[232:235], v[184:187], v[32:35]
	v_mfma_f32_16x16x32_bf16 v[24:27], v[240:243], v[184:187], v[24:27]
	v_mfma_f32_16x16x32_bf16 v[16:19], v[232:235], v[216:219], v[16:19]
	v_mfma_f32_16x16x32_bf16 v[8:11], v[240:243], v[216:219], v[8:11]
	v_mfma_f32_16x16x32_bf16 v[4:7], v[232:235], v[224:227], v[4:7]
	v_mfma_f32_16x16x32_bf16 v[0:3], v[240:243], v[224:227], v[0:3]
	s_setprio 0
	s_add_i32 s12, 0, 0x18000
	s_barrier
	s_add_u32 s10, s10, s58
	s_addc_u32 s11, s11, 0
	s_mov_b32 m0, s24
	v_lshl_add_u64 v[228:229], s[10:11], 0, v[132:133]
	ds_read_b128 v[172:175], v155 offset:32768
	ds_read_b128 v[180:183], v155 offset:34816
	ds_read_b128 v[188:191], v155 offset:36864
	ds_read_b128 v[220:223], v155 offset:38912
	ds_read_b128 v[176:179], v155 offset:33792
	ds_read_b128 v[184:187], v155 offset:35840
	ds_read_b128 v[216:219], v155 offset:37888
	ds_read_b128 v[224:227], v155 offset:39936
	global_load_lds_dwordx4 v[228:229], off
	v_lshl_add_u64 v[228:229], s[10:11], 0, v[128:129]
	s_mov_b32 m0, s25
	s_nop 0
	global_load_lds_dwordx4 v[228:229], off
	s_waitcnt lgkmcnt(8)
	s_waitcnt vmcnt(10)
	s_barrier
	s_waitcnt lgkmcnt(4)
	s_setprio 1
	v_mfma_f32_16x16x32_bf16 v[124:127], v[156:159], v[172:175], v[124:127]
	v_mfma_f32_16x16x32_bf16 v[120:123], v[164:167], v[172:175], v[120:123]
	v_mfma_f32_16x16x32_bf16 v[116:119], v[156:159], v[180:183], v[116:119]
	v_mfma_f32_16x16x32_bf16 v[108:111], v[164:167], v[180:183], v[108:111]
	v_mfma_f32_16x16x32_bf16 v[100:103], v[156:159], v[188:191], v[100:103]
	v_mfma_f32_16x16x32_bf16 v[92:95], v[164:167], v[188:191], v[92:95]
	v_mfma_f32_16x16x32_bf16 v[84:87], v[156:159], v[220:223], v[84:87]
	v_mfma_f32_16x16x32_bf16 v[76:79], v[164:167], v[220:223], v[76:79]
	s_waitcnt lgkmcnt(0)
	v_mfma_f32_16x16x32_bf16 v[124:127], v[160:163], v[176:179], v[124:127]
	v_mfma_f32_16x16x32_bf16 v[120:123], v[168:171], v[176:179], v[120:123]
	v_mfma_f32_16x16x32_bf16 v[116:119], v[160:163], v[184:187], v[116:119]
	v_mfma_f32_16x16x32_bf16 v[108:111], v[168:171], v[184:187], v[108:111]
	v_mfma_f32_16x16x32_bf16 v[100:103], v[160:163], v[216:219], v[100:103]
	v_mfma_f32_16x16x32_bf16 v[92:95], v[168:171], v[216:219], v[92:95]
	v_mfma_f32_16x16x32_bf16 v[84:87], v[160:163], v[224:227], v[84:87]
	v_mfma_f32_16x16x32_bf16 v[76:79], v[168:171], v[224:227], v[76:79]
	s_setprio 0
	s_barrier
	s_add_i32 s10, 0, 0x1c000
	s_add_i32 s11, s12, s19
	v_add_u32_e32 v200, s10, v154
	v_lshl_add_u64 v[152:153], v[152:153], 0, s[66:67]
	s_mov_b32 m0, s11
	ds_read_b128 v[228:231], v200
	ds_read_b128 v[236:239], v200 offset:2048
	ds_read_b128 v[232:235], v200 offset:1024
	ds_read_b128 v[240:243], v200 offset:3072
	global_load_lds_dwordx4 v[152:153], off
	v_lshl_add_u64 v[152:153], v[244:245], 0, s[66:67]
	s_add_i32 m0, s11, 0x2000
	s_nop 0
	global_load_lds_dwordx4 v[152:153], off
	s_waitcnt vmcnt(10)
	s_barrier
	s_waitcnt lgkmcnt(2)
	s_setprio 1
	v_mfma_f32_16x16x32_bf16 v[112:115], v[228:231], v[172:175], v[112:115]
	v_mfma_f32_16x16x32_bf16 v[104:107], v[236:239], v[172:175], v[104:107]
	v_mfma_f32_16x16x32_bf16 v[96:99], v[228:231], v[180:183], v[96:99]
	v_mfma_f32_16x16x32_bf16 v[88:91], v[236:239], v[180:183], v[88:91]
	v_mfma_f32_16x16x32_bf16 v[80:83], v[228:231], v[188:191], v[80:83]
	v_mfma_f32_16x16x32_bf16 v[72:75], v[236:239], v[188:191], v[72:75]
	v_mfma_f32_16x16x32_bf16 v[68:71], v[228:231], v[220:223], v[68:71]
	v_mfma_f32_16x16x32_bf16 v[64:67], v[236:239], v[220:223], v[64:67]
	s_waitcnt lgkmcnt(0)
	v_mfma_f32_16x16x32_bf16 v[112:115], v[232:235], v[176:179], v[112:115]
	v_mfma_f32_16x16x32_bf16 v[104:107], v[240:243], v[176:179], v[104:107]
	v_mfma_f32_16x16x32_bf16 v[96:99], v[232:235], v[184:187], v[96:99]
	v_mfma_f32_16x16x32_bf16 v[88:91], v[240:243], v[184:187], v[88:91]
	v_mfma_f32_16x16x32_bf16 v[80:83], v[232:235], v[216:219], v[80:83]
	v_mfma_f32_16x16x32_bf16 v[72:75], v[240:243], v[216:219], v[72:75]
	v_mfma_f32_16x16x32_bf16 v[68:71], v[232:235], v[224:227], v[68:71]
	v_mfma_f32_16x16x32_bf16 v[64:67], v[240:243], v[224:227], v[64:67]
	s_setprio 0
	s_mov_b32 m0, s26
	v_lshl_add_u64 v[152:153], v[246:247], 0, s[66:67]
	s_barrier
	ds_read_b128 v[172:175], v155 offset:49152
	ds_read_b128 v[180:183], v155 offset:51200
	ds_read_b128 v[188:191], v155 offset:53248
	ds_read_b128 v[220:223], v155 offset:55296
	ds_read_b128 v[176:179], v155 offset:50176
	ds_read_b128 v[184:187], v155 offset:52224
	ds_read_b128 v[216:219], v155 offset:54272
	ds_read_b128 v[224:227], v155 offset:56320
	global_load_lds_dwordx4 v[152:153], off
	v_lshl_add_u64 v[152:153], v[248:249], 0, s[66:67]
	s_mov_b32 m0, s27
	s_nop 0
	global_load_lds_dwordx4 v[152:153], off
	s_waitcnt vmcnt(10)
	s_barrier
	s_waitcnt lgkmcnt(4)
	s_setprio 1
	v_mfma_f32_16x16x32_bf16 v[60:63], v[156:159], v[172:175], v[60:63]
	v_mfma_f32_16x16x32_bf16 v[56:59], v[164:167], v[172:175], v[56:59]
	v_mfma_f32_16x16x32_bf16 v[52:55], v[156:159], v[180:183], v[52:55]
	v_mfma_f32_16x16x32_bf16 v[44:47], v[164:167], v[180:183], v[44:47]
	v_mfma_f32_16x16x32_bf16 v[36:39], v[156:159], v[188:191], v[36:39]
	v_mfma_f32_16x16x32_bf16 v[28:31], v[164:167], v[188:191], v[28:31]
	v_mfma_f32_16x16x32_bf16 v[20:23], v[156:159], v[220:223], v[20:23]
	v_mfma_f32_16x16x32_bf16 v[12:15], v[164:167], v[220:223], v[12:15]
	s_waitcnt lgkmcnt(0)
	v_mfma_f32_16x16x32_bf16 v[60:63], v[160:163], v[176:179], v[60:63]
	v_mfma_f32_16x16x32_bf16 v[56:59], v[168:171], v[176:179], v[56:59]
	v_mfma_f32_16x16x32_bf16 v[52:55], v[160:163], v[184:187], v[52:55]
	v_mfma_f32_16x16x32_bf16 v[44:47], v[168:171], v[184:187], v[44:47]
	v_mfma_f32_16x16x32_bf16 v[36:39], v[160:163], v[216:219], v[36:39]
	v_mfma_f32_16x16x32_bf16 v[28:31], v[168:171], v[216:219], v[28:31]
	v_mfma_f32_16x16x32_bf16 v[20:23], v[160:163], v[224:227], v[20:23]
	v_mfma_f32_16x16x32_bf16 v[12:15], v[168:171], v[224:227], v[12:15]
	s_setprio 0
	s_barrier
	s_add_i32 s10, s10, s19
	v_lshl_add_u64 v[152:153], v[250:251], 0, s[66:67]
	s_mov_b32 m0, s10
	s_nop 0
	global_load_lds_dwordx4 v[152:153], off
	v_lshl_add_u64 v[152:153], v[252:253], 0, s[66:67]
	s_add_i32 m0, s10, 0x2000
	s_nop 0
	global_load_lds_dwordx4 v[152:153], off
	v_add_u32_e32 v168, 0x10000, v154
	ds_read_b128 v[156:159], v168
	ds_read_b128 v[160:163], v168 offset:1024
	ds_read_b128 v[164:167], v168 offset:2048
	ds_read_b128 v[168:171], v168 offset:3072
	s_waitcnt vmcnt(10)
	s_barrier
	s_setprio 1
	v_mfma_f32_16x16x32_bf16 v[48:51], v[228:231], v[172:175], v[48:51]
	v_mfma_f32_16x16x32_bf16 v[40:43], v[236:239], v[172:175], v[40:43]
	v_mfma_f32_16x16x32_bf16 v[32:35], v[228:231], v[180:183], v[32:35]
	v_mfma_f32_16x16x32_bf16 v[24:27], v[236:239], v[180:183], v[24:27]
	v_mfma_f32_16x16x32_bf16 v[16:19], v[228:231], v[188:191], v[16:19]
	v_mfma_f32_16x16x32_bf16 v[8:11], v[236:239], v[188:191], v[8:11]
	v_mfma_f32_16x16x32_bf16 v[4:7], v[228:231], v[220:223], v[4:7]
	v_mfma_f32_16x16x32_bf16 v[0:3], v[236:239], v[220:223], v[0:3]
	v_mfma_f32_16x16x32_bf16 v[48:51], v[232:235], v[176:179], v[48:51]
	v_mfma_f32_16x16x32_bf16 v[40:43], v[240:243], v[176:179], v[40:43]
	v_mfma_f32_16x16x32_bf16 v[32:35], v[232:235], v[184:187], v[32:35]
	v_mfma_f32_16x16x32_bf16 v[24:27], v[240:243], v[184:187], v[24:27]
	v_mfma_f32_16x16x32_bf16 v[16:19], v[232:235], v[216:219], v[16:19]
	v_mfma_f32_16x16x32_bf16 v[8:11], v[240:243], v[216:219], v[8:11]
	v_mfma_f32_16x16x32_bf16 v[4:7], v[232:235], v[224:227], v[4:7]
	v_mfma_f32_16x16x32_bf16 v[0:3], v[240:243], v[224:227], v[0:3]
	s_setprio 0
	s_add_u32 s8, s8, 0x100
	s_addc_u32 s9, s9, 0
	s_add_u32 s38, s38, 0x100
	s_addc_u32 s39, s39, 0
	s_cmp_ge_u32 s40, s28
	s_mov_b32 s10, s40
	s_barrier
	s_cbranch_scc0 .LBB0_1234
	s_waitcnt lgkmcnt(0)
	v_mov_b32_e32 v152, v135
	s_mov_b64 s[8:9], s[0:1]
	v_readfirstlane_b32 s10, v152
	s_ashr_i32 s12, s10, 2
	s_load_dwordx2 s[8:9], s[8:9], 0x88
	s_lshl_b32 s11, s36, 8
	s_andn2_b32 s12, s12, 63
	s_lshr_b32 s10, s10, 1
	s_add_i32 s12, s12, s11
	s_lshl_b32 s11, s37, 8
	s_and_b32 s10, s10, 0x60
	v_and_or_b32 v156, v152, 15, s12
	s_or_b32 s10, s10, s11
	v_lshrrev_b32_e32 v152, 1, v152
	v_and_or_b32 v152, v152, 24, s10
	v_ashrrev_i32_e32 v153, 31, v152
	s_waitcnt lgkmcnt(0)
	v_lshl_add_u64 v[152:153], v[152:153], 1, s[8:9]
	s_mov_b64 s[8:9], 0x62a4400
	v_ashrrev_i32_e32 v157, 31, v156
	v_lshl_add_u64 v[158:159], v[152:153], 0, s[8:9]
	v_lshlrev_b64 v[152:153], 11, v[156:157]
	v_lshl_add_u64 v[152:153], v[158:159], 0, v[152:153]
	s_mov_b64 s[8:9], 0x40000
	v_cvt_pk_bf16_f32 v68, v68, v69
	v_cvt_pk_bf16_f32 v69, v70, v71
	v_cvt_pk_bf16_f32 v70, v64, v65
	v_lshl_add_u64 v[64:65], v[152:153], 0, s[8:9]
	s_mov_b32 s8, 0x40000
	v_cvt_pk_bf16_f32 v60, v60, v61
	v_cvt_pk_bf16_f32 v61, v62, v63
	v_cvt_pk_bf16_f32 v62, v56, v57
	v_add_co_u32_e32 v56, vcc, s8, v152
	v_cvt_pk_bf16_f32 v48, v48, v49
	v_cvt_pk_bf16_f32 v49, v50, v51
	s_mov_b64 s[8:9], 0x48000
	s_nop 0
	v_addc_co_u32_e32 v57, vcc, 0, v153, vcc
	v_cvt_pk_bf16_f32 v50, v40, v41
	v_cvt_pk_bf16_f32 v51, v42, v43
	global_store_dwordx4 v[64:65], v[48:51], off offset:256 sc1
	v_cvt_pk_bf16_f32 v42, v44, v45
	v_cvt_pk_bf16_f32 v32, v32, v33
	v_cvt_pk_bf16_f32 v33, v34, v35
	v_cvt_pk_bf16_f32 v112, v112, v113
	v_cvt_pk_bf16_f32 v113, v114, v115
	s_nop 1
	v_lshl_add_u64 v[48:49], v[152:153], 0, s[8:9]
	s_mov_b32 s8, 0x48000
	v_add_co_u32_e32 v44, vcc, s8, v152
	s_mov_b64 s[8:9], 0x50000
	v_cvt_pk_bf16_f32 v114, v104, v105
	v_or_b32_e32 v104, 16, v156
	v_addc_co_u32_e32 v45, vcc, 0, v153, vcc
	v_cvt_pk_bf16_f32 v34, v24, v25
	v_cvt_pk_bf16_f32 v35, v26, v27
	global_store_dwordx4 v[48:49], v[32:35], off offset:256 sc1
	v_ashrrev_i32_e32 v105, 31, v104
	v_cvt_pk_bf16_f32 v96, v96, v97
	v_cvt_pk_bf16_f32 v97, v98, v99
	v_cvt_pk_bf16_f32 v98, v88, v89
	v_or_b32_e32 v88, 32, v156
	v_lshl_add_u64 v[32:33], v[152:153], 0, s[8:9]
	s_mov_b32 s8, 0x50000
	v_cvt_pk_bf16_f32 v26, v28, v29
	v_add_co_u32_e32 v28, vcc, s8, v152
	v_cvt_pk_bf16_f32 v16, v16, v17
	v_cvt_pk_bf16_f32 v17, v18, v19
	s_mov_b64 s[8:9], 0x58000
	v_lshlrev_b64 v[104:105], 11, v[104:105]
	v_ashrrev_i32_e32 v89, 31, v88
	v_cvt_pk_bf16_f32 v80, v80, v81
	v_cvt_pk_bf16_f32 v81, v82, v83
	v_cvt_pk_bf16_f32 v82, v72, v73
	v_or_b32_e32 v72, 48, v156
	v_addc_co_u32_e32 v29, vcc, 0, v153, vcc
	v_cvt_pk_bf16_f32 v18, v8, v9
	v_cvt_pk_bf16_f32 v19, v10, v11
	global_store_dwordx4 v[32:33], v[16:19], off offset:256 sc1
	v_cvt_pk_bf16_f32 v115, v106, v107
	global_store_dwordx4 v[152:153], v[112:115], off offset:256 sc1
	v_lshlrev_b64 v[88:89], 11, v[88:89]
	v_lshl_add_u64 v[16:17], v[152:153], 0, s[8:9]
	s_mov_b32 s8, 0x58000
	v_lshl_add_u64 v[112:113], v[158:159], 0, v[104:105]
	v_ashrrev_i32_e32 v73, 31, v72
	v_cvt_pk_bf16_f32 v10, v12, v13
	v_add_co_u32_e32 v12, vcc, s8, v152
	v_cvt_pk_bf16_f32 v99, v90, v91
	global_store_dwordx4 v[112:113], v[96:99], off offset:256 sc1
	v_lshlrev_b64 v[72:73], 11, v[72:73]
	v_addc_co_u32_e32 v13, vcc, 0, v153, vcc
	v_lshl_add_u64 v[96:97], v[158:159], 0, v[88:89]
	v_cvt_pk_bf16_f32 v83, v74, v75
	global_store_dwordx4 v[96:97], v[80:83], off offset:256 sc1
	s_and_b64 vcc, exec, s[4:5]
	s_mov_b32 s37, s34
	v_lshl_add_u64 v[80:81], v[158:159], 0, v[72:73]
	s_mov_b32 s36, s35
	s_mov_b64 s[10:11], s[6:7]
	s_mov_b64 s[12:13], s[2:3]
	v_cvt_pk_bf16_f32 v124, v124, v125
	v_cvt_pk_bf16_f32 v125, v126, v127
	v_cvt_pk_bf16_f32 v126, v120, v121
	v_cvt_pk_bf16_f32 v127, v122, v123
	global_store_dwordx4 v[152:153], v[124:127], off sc1
	v_cvt_pk_bf16_f32 v104, v116, v117
	v_cvt_pk_bf16_f32 v105, v118, v119
	v_cvt_pk_bf16_f32 v106, v108, v109
	v_cvt_pk_bf16_f32 v107, v110, v111
	global_store_dwordx4 v[112:113], v[104:107], off sc1
	v_cvt_pk_bf16_f32 v88, v100, v101
	v_cvt_pk_bf16_f32 v89, v102, v103
	v_cvt_pk_bf16_f32 v90, v92, v93
	v_cvt_pk_bf16_f32 v91, v94, v95
	global_store_dwordx4 v[96:97], v[88:91], off sc1
	v_cvt_pk_bf16_f32 v72, v84, v85
	v_cvt_pk_bf16_f32 v73, v86, v87
	v_cvt_pk_bf16_f32 v74, v76, v77
	v_cvt_pk_bf16_f32 v75, v78, v79
	global_store_dwordx4 v[80:81], v[72:75], off sc1
	v_cvt_pk_bf16_f32 v71, v66, v67
	global_store_dwordx4 v[80:81], v[68:71], off offset:256 sc1
	v_cvt_pk_bf16_f32 v63, v58, v59
	global_store_dwordx4 v[56:57], v[60:63], off sc1
	v_cvt_pk_bf16_f32 v40, v52, v53
	v_cvt_pk_bf16_f32 v41, v54, v55
	v_cvt_pk_bf16_f32 v43, v46, v47
	global_store_dwordx4 v[44:45], v[40:43], off sc1
	v_cvt_pk_bf16_f32 v24, v36, v37
	v_cvt_pk_bf16_f32 v25, v38, v39
	v_cvt_pk_bf16_f32 v27, v30, v31
	global_store_dwordx4 v[28:29], v[24:27], off sc1
	v_cvt_pk_bf16_f32 v8, v20, v21
	v_cvt_pk_bf16_f32 v9, v22, v23
	v_cvt_pk_bf16_f32 v11, v14, v15
	global_store_dwordx4 v[12:13], v[8:11], off sc1
	v_cvt_pk_bf16_f32 v4, v4, v5
	v_cvt_pk_bf16_f32 v5, v6, v7
	v_cvt_pk_bf16_f32 v6, v0, v1
	v_cvt_pk_bf16_f32 v7, v2, v3
	global_store_dwordx4 v[16:17], v[4:7], off offset:256 sc1
	s_cbranch_vccz .LBB0_1223
	s_waitcnt vmcnt(0)
	s_cmpk_gt_u32 s14, 0xff
	s_cbranch_scc1 .LBB0_1238
	s_barrier
